# P1W: in-proj pair GEMM half-steps start their first four MFMAs as soon as those fragments arrive (counted lgkmcnt); the read-completion wait + LDS-release barrier and the DMA pieces follow
# speedup vs baseline: 1.0022x; 1.0022x over previous
.Lg1_loop:
	ds_read_b128 v[92:95], v84 offset:0
	ds_read_b128 v[96:99], v84 offset:4096
	ds_read_b128 v[188:191], v85 offset:0
	ds_read_b128 v[192:195], v85 offset:4096
	ds_read_b128 v[100:103], v86 offset:0
	ds_read_b128 v[144:147], v86 offset:4096
	ds_read_b128 v[212:215], v87 offset:0
	ds_read_b128 v[216:219], v87 offset:4096
	ds_read_b128 v[148:151], v88 offset:0
	ds_read_b128 v[152:155], v88 offset:4096
	ds_read_b128 v[220:223], v89 offset:0
	ds_read_b128 v[224:227], v89 offset:4096
	ds_read_b128 v[180:183], v90 offset:0
	ds_read_b128 v[184:187], v90 offset:4096
	ds_read_b128 v[228:231], v91 offset:0
	ds_read_b128 v[252:255], v91 offset:4096
	s_waitcnt lgkmcnt(12)
	v_mfma_f32_32x32x16_bf16 v[18:33], v[92:95], v[188:191], v[18:33]
	v_mfma_f32_32x32x16_bf16 v[50:65], v[92:95], v[192:195], v[50:65]
	v_mfma_f32_32x32x16_bf16 v[2:17], v[96:99], v[188:191], v[2:17]
	v_mfma_f32_32x32x16_bf16 v[34:49], v[96:99], v[192:195], v[34:49]
	s_waitcnt lgkmcnt(0)
	s_barrier
	s_mov_b32 m0, s1
	v_mfma_f32_32x32x16_bf16 v[18:33], v[100:103], v[212:215], v[18:33]
	global_load_lds_dwordx4 v[66:67], off
	v_mfma_f32_32x32x16_bf16 v[50:65], v[100:103], v[216:219], v[50:65]
	s_add_i32 m0, s1, 0x400
	v_mfma_f32_32x32x16_bf16 v[2:17], v[144:147], v[212:215], v[2:17]
	global_load_lds_dwordx4 v[70:71], off
	s_add_i32 m0, s1, 0x800
	v_mfma_f32_32x32x16_bf16 v[34:49], v[144:147], v[216:219], v[34:49]
	global_load_lds_dwordx4 v[74:75], off
	v_mfma_f32_32x32x16_bf16 v[18:33], v[148:151], v[220:223], v[18:33]
	s_add_i32 m0, s1, 0xc00
	v_mfma_f32_32x32x16_bf16 v[50:65], v[148:151], v[224:227], v[50:65]
	global_load_lds_dwordx4 v[78:79], off
	v_mfma_f32_32x32x16_bf16 v[2:17], v[152:155], v[220:223], v[2:17]
	v_mfma_f32_32x32x16_bf16 v[34:49], v[152:155], v[224:227], v[34:49]
	s_mov_b32 m0, s8
	v_mfma_f32_32x32x16_bf16 v[18:33], v[180:183], v[228:231], v[18:33]
	global_load_lds_dwordx4 v[68:69], off
	v_lshl_add_u64 v[68:69], v[68:69], 0, s[34:35]
	s_mov_b32 m0, s9
	v_mfma_f32_32x32x16_bf16 v[50:65], v[180:183], v[252:255], v[50:65]
	global_load_lds_dwordx4 v[72:73], off
	v_lshl_add_u64 v[72:73], v[72:73], 0, s[34:35]
	v_mfma_f32_32x32x16_bf16 v[2:17], v[184:187], v[228:231], v[2:17]
	v_mfma_f32_32x32x16_bf16 v[34:49], v[184:187], v[252:255], v[34:49]
	s_waitcnt vmcnt(6)
	s_barrier
	ds_read_b128 v[92:95], v84 offset:32768
	ds_read_b128 v[96:99], v84 offset:36864
	ds_read_b128 v[100:103], v86 offset:32768
	ds_read_b128 v[144:147], v86 offset:36864
	ds_read_b128 v[148:151], v88 offset:32768
	ds_read_b128 v[152:155], v88 offset:36864
	ds_read_b128 v[180:183], v90 offset:32768
	ds_read_b128 v[184:187], v90 offset:36864
	s_waitcnt lgkmcnt(6)
	v_mfma_f32_32x32x16_bf16 v[104:119], v[92:95], v[188:191], v[104:119]
	v_mfma_f32_32x32x16_bf16 v[128:143], v[92:95], v[192:195], v[128:143]
	v_mfma_f32_32x32x16_bf16 v[196:211], v[96:99], v[188:191], v[196:211]
	v_mfma_f32_32x32x16_bf16 v[236:251], v[96:99], v[192:195], v[236:251]
	s_waitcnt lgkmcnt(0)
	s_barrier
	s_mov_b32 m0, s6
	v_lshl_add_u64 v[82:83], v[66:67], 0, s[26:27]
	v_mfma_f32_32x32x16_bf16 v[104:119], v[100:103], v[212:215], v[104:119]
	global_load_lds_dwordx4 v[82:83], off
	v_lshl_add_u64 v[66:67], v[66:67], 0, s[34:35]
	v_mfma_f32_32x32x16_bf16 v[128:143], v[100:103], v[216:219], v[128:143]
	s_mov_b32 m0, s13
	v_lshl_add_u64 v[82:83], v[70:71], 0, s[26:27]
	v_mfma_f32_32x32x16_bf16 v[196:211], v[144:147], v[212:215], v[196:211]
	global_load_lds_dwordx4 v[82:83], off
	v_lshl_add_u64 v[70:71], v[70:71], 0, s[34:35]
	s_mov_b32 m0, s15
	v_lshl_add_u64 v[82:83], v[74:75], 0, s[26:27]
	v_mfma_f32_32x32x16_bf16 v[236:251], v[144:147], v[216:219], v[236:251]
	global_load_lds_dwordx4 v[82:83], off
	v_lshl_add_u64 v[74:75], v[74:75], 0, s[34:35]
	v_mfma_f32_32x32x16_bf16 v[104:119], v[148:151], v[220:223], v[104:119]
	s_mov_b32 m0, s17
	v_lshl_add_u64 v[82:83], v[78:79], 0, s[26:27]
	v_mfma_f32_32x32x16_bf16 v[128:143], v[148:151], v[224:227], v[128:143]
	global_load_lds_dwordx4 v[82:83], off
	v_lshl_add_u64 v[78:79], v[78:79], 0, s[34:35]
	v_mfma_f32_32x32x16_bf16 v[196:211], v[152:155], v[220:223], v[196:211]
	v_mfma_f32_32x32x16_bf16 v[236:251], v[152:155], v[224:227], v[236:251]
	s_mov_b32 m0, s10
	v_mfma_f32_32x32x16_bf16 v[104:119], v[180:183], v[228:231], v[104:119]
	global_load_lds_dwordx4 v[76:77], off
	v_lshl_add_u64 v[76:77], v[76:77], 0, s[34:35]
	s_mov_b32 m0, s11
	v_mfma_f32_32x32x16_bf16 v[128:143], v[180:183], v[252:255], v[128:143]
	global_load_lds_dwordx4 v[80:81], off
	v_lshl_add_u64 v[80:81], v[80:81], 0, s[34:35]
	v_mfma_f32_32x32x16_bf16 v[196:211], v[184:187], v[228:231], v[196:211]
	v_mfma_f32_32x32x16_bf16 v[236:251], v[184:187], v[252:255], v[236:251]
	s_waitcnt vmcnt(6)
	s_barrier
	ds_read_b128 v[92:95], v84 offset:0
	ds_read_b128 v[96:99], v84 offset:4096
	ds_read_b128 v[188:191], v85 offset:32768
	ds_read_b128 v[192:195], v85 offset:36864
	ds_read_b128 v[100:103], v86 offset:0
	ds_read_b128 v[144:147], v86 offset:4096
	ds_read_b128 v[212:215], v87 offset:32768
	ds_read_b128 v[216:219], v87 offset:36864
	ds_read_b128 v[148:151], v88 offset:0
	ds_read_b128 v[152:155], v88 offset:4096
	ds_read_b128 v[220:223], v89 offset:32768
	ds_read_b128 v[224:227], v89 offset:36864
	ds_read_b128 v[180:183], v90 offset:0
	ds_read_b128 v[184:187], v90 offset:4096
	ds_read_b128 v[228:231], v91 offset:32768
	ds_read_b128 v[252:255], v91 offset:36864
	s_waitcnt lgkmcnt(12)
	v_mfma_f32_32x32x16_bf16 v[18:33], v[92:95], v[188:191], v[18:33]
	v_mfma_f32_32x32x16_bf16 v[50:65], v[92:95], v[192:195], v[50:65]
	v_mfma_f32_32x32x16_bf16 v[2:17], v[96:99], v[188:191], v[2:17]
	v_mfma_f32_32x32x16_bf16 v[34:49], v[96:99], v[192:195], v[34:49]
	s_waitcnt lgkmcnt(0)
	s_barrier
	s_mov_b32 m0, s1
	v_mfma_f32_32x32x16_bf16 v[18:33], v[100:103], v[212:215], v[18:33]
	global_load_lds_dwordx4 v[66:67], off
	v_mfma_f32_32x32x16_bf16 v[50:65], v[100:103], v[216:219], v[50:65]
	s_add_i32 m0, s1, 0x400
	v_mfma_f32_32x32x16_bf16 v[2:17], v[144:147], v[212:215], v[2:17]
	global_load_lds_dwordx4 v[70:71], off
	s_add_i32 m0, s1, 0x800
	v_mfma_f32_32x32x16_bf16 v[34:49], v[144:147], v[216:219], v[34:49]
	global_load_lds_dwordx4 v[74:75], off
	v_mfma_f32_32x32x16_bf16 v[18:33], v[148:151], v[220:223], v[18:33]
	s_add_i32 m0, s1, 0xc00
	v_mfma_f32_32x32x16_bf16 v[50:65], v[148:151], v[224:227], v[50:65]
	global_load_lds_dwordx4 v[78:79], off
	v_mfma_f32_32x32x16_bf16 v[2:17], v[152:155], v[220:223], v[2:17]
	v_mfma_f32_32x32x16_bf16 v[34:49], v[152:155], v[224:227], v[34:49]
	s_mov_b32 m0, s7
	v_mfma_f32_32x32x16_bf16 v[18:33], v[180:183], v[228:231], v[18:33]
	global_load_lds_dwordx4 v[68:69], off
	v_lshl_add_u64 v[68:69], v[68:69], 0, s[34:35]
	s_mov_b32 m0, s14
	v_mfma_f32_32x32x16_bf16 v[50:65], v[180:183], v[252:255], v[50:65]
	global_load_lds_dwordx4 v[72:73], off
	v_lshl_add_u64 v[72:73], v[72:73], 0, s[34:35]
	v_mfma_f32_32x32x16_bf16 v[2:17], v[184:187], v[228:231], v[2:17]
	v_mfma_f32_32x32x16_bf16 v[34:49], v[184:187], v[252:255], v[34:49]
	s_waitcnt vmcnt(6)
	s_barrier
	ds_read_b128 v[92:95], v84 offset:32768
	ds_read_b128 v[96:99], v84 offset:36864
	ds_read_b128 v[100:103], v86 offset:32768
	ds_read_b128 v[144:147], v86 offset:36864
	ds_read_b128 v[148:151], v88 offset:32768
	ds_read_b128 v[152:155], v88 offset:36864
	ds_read_b128 v[180:183], v90 offset:32768
	ds_read_b128 v[184:187], v90 offset:36864
	s_waitcnt lgkmcnt(6)
	v_mfma_f32_32x32x16_bf16 v[104:119], v[92:95], v[188:191], v[104:119]
	v_mfma_f32_32x32x16_bf16 v[128:143], v[92:95], v[192:195], v[128:143]
	v_mfma_f32_32x32x16_bf16 v[196:211], v[96:99], v[188:191], v[196:211]
	v_mfma_f32_32x32x16_bf16 v[236:251], v[96:99], v[192:195], v[236:251]
	s_waitcnt lgkmcnt(0)
	s_barrier
	s_mov_b32 m0, s6
	v_lshl_add_u64 v[82:83], v[66:67], 0, s[26:27]
	v_mfma_f32_32x32x16_bf16 v[104:119], v[100:103], v[212:215], v[104:119]
	global_load_lds_dwordx4 v[82:83], off
	v_lshl_add_u64 v[66:67], v[66:67], 0, s[34:35]
	v_mfma_f32_32x32x16_bf16 v[128:143], v[100:103], v[216:219], v[128:143]
	s_mov_b32 m0, s13
	v_lshl_add_u64 v[82:83], v[70:71], 0, s[26:27]
	v_mfma_f32_32x32x16_bf16 v[196:211], v[144:147], v[212:215], v[196:211]
	global_load_lds_dwordx4 v[82:83], off
	v_lshl_add_u64 v[70:71], v[70:71], 0, s[34:35]
	s_mov_b32 m0, s15
	v_lshl_add_u64 v[82:83], v[74:75], 0, s[26:27]
	v_mfma_f32_32x32x16_bf16 v[236:251], v[144:147], v[216:219], v[236:251]
	global_load_lds_dwordx4 v[82:83], off
	v_lshl_add_u64 v[74:75], v[74:75], 0, s[34:35]
	v_mfma_f32_32x32x16_bf16 v[104:119], v[148:151], v[220:223], v[104:119]
	s_mov_b32 m0, s17
	v_lshl_add_u64 v[82:83], v[78:79], 0, s[26:27]
	v_mfma_f32_32x32x16_bf16 v[128:143], v[148:151], v[224:227], v[128:143]
	global_load_lds_dwordx4 v[82:83], off
	v_lshl_add_u64 v[78:79], v[78:79], 0, s[34:35]
	v_mfma_f32_32x32x16_bf16 v[196:211], v[152:155], v[220:223], v[196:211]
	v_mfma_f32_32x32x16_bf16 v[236:251], v[152:155], v[224:227], v[236:251]
	s_mov_b32 m0, s16
	v_mfma_f32_32x32x16_bf16 v[104:119], v[180:183], v[228:231], v[104:119]
	global_load_lds_dwordx4 v[76:77], off
	v_lshl_add_u64 v[76:77], v[76:77], 0, s[34:35]
	s_mov_b32 m0, s25
	v_mfma_f32_32x32x16_bf16 v[128:143], v[180:183], v[252:255], v[128:143]
	global_load_lds_dwordx4 v[80:81], off
	v_lshl_add_u64 v[80:81], v[80:81], 0, s[34:35]
	v_mfma_f32_32x32x16_bf16 v[196:211], v[184:187], v[228:231], v[196:211]
	v_mfma_f32_32x32x16_bf16 v[236:251], v[184:187], v[252:255], v[236:251]
	s_waitcnt vmcnt(6)
	s_barrier
	s_add_i32 s12, s12, 2
	s_cmp_lt_u32 s12, 14
	s_cbranch_scc1 .Lg1_loop
	ds_read_b128 v[92:95], v84 offset:0
	ds_read_b128 v[96:99], v84 offset:4096
	ds_read_b128 v[188:191], v85 offset:0
	ds_read_b128 v[192:195], v85 offset:4096
	ds_read_b128 v[100:103], v86 offset:0
	ds_read_b128 v[144:147], v86 offset:4096
	ds_read_b128 v[212:215], v87 offset:0
	ds_read_b128 v[216:219], v87 offset:4096
	ds_read_b128 v[148:151], v88 offset:0
	ds_read_b128 v[152:155], v88 offset:4096
	ds_read_b128 v[220:223], v89 offset:0
	ds_read_b128 v[224:227], v89 offset:4096
	ds_read_b128 v[180:183], v90 offset:0
	ds_read_b128 v[184:187], v90 offset:4096
	ds_read_b128 v[228:231], v91 offset:0
	ds_read_b128 v[252:255], v91 offset:4096
	s_waitcnt lgkmcnt(12)
	v_mfma_f32_32x32x16_bf16 v[18:33], v[92:95], v[188:191], v[18:33]
	v_mfma_f32_32x32x16_bf16 v[50:65], v[92:95], v[192:195], v[50:65]
	v_mfma_f32_32x32x16_bf16 v[2:17], v[96:99], v[188:191], v[2:17]
	v_mfma_f32_32x32x16_bf16 v[34:49], v[96:99], v[192:195], v[34:49]
	s_waitcnt lgkmcnt(0)
	s_barrier
	s_mov_b32 m0, s1
	v_mfma_f32_32x32x16_bf16 v[18:33], v[100:103], v[212:215], v[18:33]
	global_load_lds_dwordx4 v[66:67], off
	v_mfma_f32_32x32x16_bf16 v[50:65], v[100:103], v[216:219], v[50:65]
	s_add_i32 m0, s1, 0x400
	v_mfma_f32_32x32x16_bf16 v[2:17], v[144:147], v[212:215], v[2:17]
	global_load_lds_dwordx4 v[70:71], off
	v_mfma_f32_32x32x16_bf16 v[34:49], v[144:147], v[216:219], v[34:49]
	v_mfma_f32_32x32x16_bf16 v[18:33], v[148:151], v[220:223], v[18:33]
	s_add_i32 m0, s1, 0x800
	v_mfma_f32_32x32x16_bf16 v[50:65], v[148:151], v[224:227], v[50:65]
	global_load_lds_dwordx4 v[74:75], off
	v_mfma_f32_32x32x16_bf16 v[2:17], v[152:155], v[220:223], v[2:17]
	v_mfma_f32_32x32x16_bf16 v[34:49], v[152:155], v[224:227], v[34:49]
	s_add_i32 m0, s1, 0xc00
	v_mfma_f32_32x32x16_bf16 v[18:33], v[180:183], v[228:231], v[18:33]
	global_load_lds_dwordx4 v[78:79], off
	v_mfma_f32_32x32x16_bf16 v[50:65], v[180:183], v[252:255], v[50:65]
	v_mfma_f32_32x32x16_bf16 v[2:17], v[184:187], v[228:231], v[2:17]
	v_mfma_f32_32x32x16_bf16 v[34:49], v[184:187], v[252:255], v[34:49]
	s_waitcnt vmcnt(4)
	s_barrier
	ds_read_b128 v[92:95], v84 offset:32768
	ds_read_b128 v[96:99], v84 offset:36864
	ds_read_b128 v[100:103], v86 offset:32768
	ds_read_b128 v[144:147], v86 offset:36864
	ds_read_b128 v[148:151], v88 offset:32768
	ds_read_b128 v[152:155], v88 offset:36864
	ds_read_b128 v[180:183], v90 offset:32768
	ds_read_b128 v[184:187], v90 offset:36864
	s_waitcnt lgkmcnt(6)
	v_mfma_f32_32x32x16_bf16 v[104:119], v[92:95], v[188:191], v[104:119]
	v_mfma_f32_32x32x16_bf16 v[128:143], v[92:95], v[192:195], v[128:143]
	v_mfma_f32_32x32x16_bf16 v[196:211], v[96:99], v[188:191], v[196:211]
	v_mfma_f32_32x32x16_bf16 v[236:251], v[96:99], v[192:195], v[236:251]
	s_waitcnt lgkmcnt(0)
	s_barrier
	s_mov_b32 m0, s6
	v_lshl_add_u64 v[82:83], v[66:67], 0, s[26:27]
	v_mfma_f32_32x32x16_bf16 v[104:119], v[100:103], v[212:215], v[104:119]
	global_load_lds_dwordx4 v[82:83], off
	v_lshl_add_u64 v[66:67], v[66:67], 0, s[34:35]
	v_mfma_f32_32x32x16_bf16 v[128:143], v[100:103], v[216:219], v[128:143]
	s_mov_b32 m0, s13
	v_lshl_add_u64 v[82:83], v[70:71], 0, s[26:27]
	v_mfma_f32_32x32x16_bf16 v[196:211], v[144:147], v[212:215], v[196:211]
	global_load_lds_dwordx4 v[82:83], off
	v_lshl_add_u64 v[70:71], v[70:71], 0, s[34:35]
	v_mfma_f32_32x32x16_bf16 v[236:251], v[144:147], v[216:219], v[236:251]
	v_mfma_f32_32x32x16_bf16 v[104:119], v[148:151], v[220:223], v[104:119]
	s_mov_b32 m0, s15
	v_lshl_add_u64 v[82:83], v[74:75], 0, s[26:27]
	v_mfma_f32_32x32x16_bf16 v[128:143], v[148:151], v[224:227], v[128:143]
	global_load_lds_dwordx4 v[82:83], off
	v_lshl_add_u64 v[74:75], v[74:75], 0, s[34:35]
	v_mfma_f32_32x32x16_bf16 v[196:211], v[152:155], v[220:223], v[196:211]
	v_mfma_f32_32x32x16_bf16 v[236:251], v[152:155], v[224:227], v[236:251]
	s_mov_b32 m0, s17
	v_lshl_add_u64 v[82:83], v[78:79], 0, s[26:27]
	v_mfma_f32_32x32x16_bf16 v[104:119], v[180:183], v[228:231], v[104:119]
	global_load_lds_dwordx4 v[82:83], off
	v_lshl_add_u64 v[78:79], v[78:79], 0, s[34:35]
	v_mfma_f32_32x32x16_bf16 v[128:143], v[180:183], v[252:255], v[128:143]
	v_mfma_f32_32x32x16_bf16 v[196:211], v[184:187], v[228:231], v[196:211]
	v_mfma_f32_32x32x16_bf16 v[236:251], v[184:187], v[252:255], v[236:251]
	s_waitcnt vmcnt(4)
	s_barrier
	ds_read_b128 v[92:95], v84 offset:0
	ds_read_b128 v[96:99], v84 offset:4096
	ds_read_b128 v[188:191], v85 offset:32768
	ds_read_b128 v[192:195], v85 offset:36864
	ds_read_b128 v[100:103], v86 offset:0
	ds_read_b128 v[144:147], v86 offset:4096
	ds_read_b128 v[212:215], v87 offset:32768
	ds_read_b128 v[216:219], v87 offset:36864
	ds_read_b128 v[148:151], v88 offset:0
	ds_read_b128 v[152:155], v88 offset:4096
	ds_read_b128 v[220:223], v89 offset:32768
	ds_read_b128 v[224:227], v89 offset:36864
	ds_read_b128 v[180:183], v90 offset:0
	ds_read_b128 v[184:187], v90 offset:4096
	ds_read_b128 v[228:231], v91 offset:32768
	ds_read_b128 v[252:255], v91 offset:36864
	s_waitcnt lgkmcnt(12)
	v_mfma_f32_32x32x16_bf16 v[18:33], v[92:95], v[188:191], v[18:33]
	v_mfma_f32_32x32x16_bf16 v[50:65], v[92:95], v[192:195], v[50:65]
	v_mfma_f32_32x32x16_bf16 v[2:17], v[96:99], v[188:191], v[2:17]
	v_mfma_f32_32x32x16_bf16 v[34:49], v[96:99], v[192:195], v[34:49]
	s_waitcnt lgkmcnt(0)
	s_barrier
	v_mfma_f32_32x32x16_bf16 v[18:33], v[100:103], v[212:215], v[18:33]
	v_mfma_f32_32x32x16_bf16 v[50:65], v[100:103], v[216:219], v[50:65]
	v_mfma_f32_32x32x16_bf16 v[2:17], v[144:147], v[212:215], v[2:17]
	v_mfma_f32_32x32x16_bf16 v[34:49], v[144:147], v[216:219], v[34:49]
	v_mfma_f32_32x32x16_bf16 v[18:33], v[148:151], v[220:223], v[18:33]
	v_mfma_f32_32x32x16_bf16 v[50:65], v[148:151], v[224:227], v[50:65]
	v_mfma_f32_32x32x16_bf16 v[2:17], v[152:155], v[220:223], v[2:17]
	v_mfma_f32_32x32x16_bf16 v[34:49], v[152:155], v[224:227], v[34:49]
	v_mfma_f32_32x32x16_bf16 v[18:33], v[180:183], v[228:231], v[18:33]
	v_mfma_f32_32x32x16_bf16 v[50:65], v[180:183], v[252:255], v[50:65]
	v_mfma_f32_32x32x16_bf16 v[2:17], v[184:187], v[228:231], v[2:17]
	v_mfma_f32_32x32x16_bf16 v[34:49], v[184:187], v[252:255], v[34:49]
	s_waitcnt vmcnt(0)
	s_barrier
	ds_read_b128 v[92:95], v84 offset:32768
	ds_read_b128 v[96:99], v84 offset:36864
	ds_read_b128 v[100:103], v86 offset:32768
	ds_read_b128 v[144:147], v86 offset:36864
	ds_read_b128 v[148:151], v88 offset:32768
	ds_read_b128 v[152:155], v88 offset:36864
	ds_read_b128 v[180:183], v90 offset:32768
	ds_read_b128 v[184:187], v90 offset:36864
	s_waitcnt lgkmcnt(6)
	v_mfma_f32_32x32x16_bf16 v[104:119], v[92:95], v[188:191], v[104:119]
	v_mfma_f32_32x32x16_bf16 v[128:143], v[92:95], v[192:195], v[128:143]
	v_mfma_f32_32x32x16_bf16 v[196:211], v[96:99], v[188:191], v[196:211]
	v_mfma_f32_32x32x16_bf16 v[236:251], v[96:99], v[192:195], v[236:251]
	s_waitcnt lgkmcnt(0)
	s_barrier
	v_mfma_f32_32x32x16_bf16 v[104:119], v[100:103], v[212:215], v[104:119]
	v_mfma_f32_32x32x16_bf16 v[128:143], v[100:103], v[216:219], v[128:143]
	v_mfma_f32_32x32x16_bf16 v[196:211], v[144:147], v[212:215], v[196:211]
	v_mfma_f32_32x32x16_bf16 v[236:251], v[144:147], v[216:219], v[236:251]
	v_mfma_f32_32x32x16_bf16 v[104:119], v[148:151], v[220:223], v[104:119]
	v_mfma_f32_32x32x16_bf16 v[128:143], v[148:151], v[224:227], v[128:143]
	v_mfma_f32_32x32x16_bf16 v[196:211], v[152:155], v[220:223], v[196:211]
	v_mfma_f32_32x32x16_bf16 v[236:251], v[152:155], v[224:227], v[236:251]
	v_mfma_f32_32x32x16_bf16 v[104:119], v[180:183], v[228:231], v[104:119]
	v_mfma_f32_32x32x16_bf16 v[128:143], v[180:183], v[252:255], v[128:143]
	v_mfma_f32_32x32x16_bf16 v[196:211], v[184:187], v[228:231], v[196:211]
	v_mfma_f32_32x32x16_bf16 v[236:251], v[184:187], v[252:255], v[236:251]
	s_waitcnt vmcnt(0) lgkmcnt(0)
	s_barrier
	s_branch .LBB0_187
.Lg1_loop_w1:
	ds_read_b128 v[92:95], v84 offset:0
	ds_read_b128 v[96:99], v84 offset:4096
	ds_read_b128 v[188:191], v85 offset:0
	ds_read_b128 v[192:195], v85 offset:4096
	ds_read_b128 v[100:103], v86 offset:0
	ds_read_b128 v[144:147], v86 offset:4096
	ds_read_b128 v[212:215], v87 offset:0
	ds_read_b128 v[216:219], v87 offset:4096
	ds_read_b128 v[148:151], v88 offset:0
	ds_read_b128 v[152:155], v88 offset:4096
	ds_read_b128 v[220:223], v89 offset:0
	ds_read_b128 v[224:227], v89 offset:4096
	ds_read_b128 v[180:183], v90 offset:0
	ds_read_b128 v[184:187], v90 offset:4096
	ds_read_b128 v[228:231], v91 offset:0
	ds_read_b128 v[252:255], v91 offset:4096
	s_waitcnt lgkmcnt(12)
	v_mfma_f32_32x32x16_bf16 v[18:33], v[92:95], v[188:191], v[18:33]
	v_mfma_f32_32x32x16_bf16 v[50:65], v[92:95], v[192:195], v[50:65]
	v_mfma_f32_32x32x16_bf16 v[2:17], v[96:99], v[188:191], v[2:17]
	v_mfma_f32_32x32x16_bf16 v[34:49], v[96:99], v[192:195], v[34:49]
	s_waitcnt lgkmcnt(0)
	s_barrier
	s_mov_b32 m0, s1
	v_mfma_f32_32x32x16_bf16 v[18:33], v[100:103], v[212:215], v[18:33]
	global_load_lds_dwordx4 v[66:67], off
	v_mfma_f32_32x32x16_bf16 v[50:65], v[100:103], v[216:219], v[50:65]
	s_add_i32 m0, s1, 0x400
	v_mfma_f32_32x32x16_bf16 v[2:17], v[144:147], v[212:215], v[2:17]
	global_load_lds_dwordx4 v[70:71], off
	v_mfma_f32_32x32x16_bf16 v[34:49], v[144:147], v[216:219], v[34:49]
	s_add_i32 m0, s1, 0x800
	v_mfma_f32_32x32x16_bf16 v[18:33], v[148:151], v[220:223], v[18:33]
	global_load_lds_dwordx4 v[74:75], off
	v_mfma_f32_32x32x16_bf16 v[50:65], v[148:151], v[224:227], v[50:65]
	s_add_i32 m0, s1, 0xc00
	v_mfma_f32_32x32x16_bf16 v[2:17], v[152:155], v[220:223], v[2:17]
	global_load_lds_dwordx4 v[78:79], off
	v_mfma_f32_32x32x16_bf16 v[34:49], v[152:155], v[224:227], v[34:49]
	s_mov_b32 m0, s8
	v_mfma_f32_32x32x16_bf16 v[18:33], v[180:183], v[228:231], v[18:33]
	global_load_lds_dwordx4 v[68:69], off
	v_lshl_add_u64 v[68:69], v[68:69], 0, s[34:35]
	v_mfma_f32_32x32x16_bf16 v[50:65], v[180:183], v[252:255], v[50:65]
	s_mov_b32 m0, s9
	v_mfma_f32_32x32x16_bf16 v[2:17], v[184:187], v[228:231], v[2:17]
	global_load_lds_dwordx4 v[72:73], off
	v_lshl_add_u64 v[72:73], v[72:73], 0, s[34:35]
	v_mfma_f32_32x32x16_bf16 v[34:49], v[184:187], v[252:255], v[34:49]
	s_waitcnt vmcnt(6)
	s_barrier
	ds_read_b128 v[92:95], v84 offset:32768
	ds_read_b128 v[96:99], v84 offset:36864
	ds_read_b128 v[100:103], v86 offset:32768
	ds_read_b128 v[144:147], v86 offset:36864
	ds_read_b128 v[148:151], v88 offset:32768
	ds_read_b128 v[152:155], v88 offset:36864
	ds_read_b128 v[180:183], v90 offset:32768
	ds_read_b128 v[184:187], v90 offset:36864
	s_waitcnt lgkmcnt(6)
	v_mfma_f32_32x32x16_bf16 v[104:119], v[92:95], v[188:191], v[104:119]
	v_mfma_f32_32x32x16_bf16 v[128:143], v[92:95], v[192:195], v[128:143]
	v_mfma_f32_32x32x16_bf16 v[196:211], v[96:99], v[188:191], v[196:211]
	v_mfma_f32_32x32x16_bf16 v[236:251], v[96:99], v[192:195], v[236:251]
	s_waitcnt lgkmcnt(0)
	s_barrier
	s_mov_b32 m0, s6
	v_lshl_add_u64 v[82:83], v[66:67], 0, s[26:27]
	v_mfma_f32_32x32x16_bf16 v[104:119], v[100:103], v[212:215], v[104:119]
	global_load_lds_dwordx4 v[82:83], off
	v_lshl_add_u64 v[66:67], v[66:67], 0, s[34:35]
	v_mfma_f32_32x32x16_bf16 v[128:143], v[100:103], v[216:219], v[128:143]
	s_mov_b32 m0, s13
	v_lshl_add_u64 v[82:83], v[70:71], 0, s[26:27]
	v_mfma_f32_32x32x16_bf16 v[196:211], v[144:147], v[212:215], v[196:211]
	global_load_lds_dwordx4 v[82:83], off
	v_lshl_add_u64 v[70:71], v[70:71], 0, s[34:35]
	v_mfma_f32_32x32x16_bf16 v[236:251], v[144:147], v[216:219], v[236:251]
	s_mov_b32 m0, s15
	v_lshl_add_u64 v[82:83], v[74:75], 0, s[26:27]
	v_mfma_f32_32x32x16_bf16 v[104:119], v[148:151], v[220:223], v[104:119]
	global_load_lds_dwordx4 v[82:83], off
	v_lshl_add_u64 v[74:75], v[74:75], 0, s[34:35]
	v_mfma_f32_32x32x16_bf16 v[128:143], v[148:151], v[224:227], v[128:143]
	s_mov_b32 m0, s17
	v_lshl_add_u64 v[82:83], v[78:79], 0, s[26:27]
	v_mfma_f32_32x32x16_bf16 v[196:211], v[152:155], v[220:223], v[196:211]
	global_load_lds_dwordx4 v[82:83], off
	v_lshl_add_u64 v[78:79], v[78:79], 0, s[34:35]
	v_mfma_f32_32x32x16_bf16 v[236:251], v[152:155], v[224:227], v[236:251]
	s_mov_b32 m0, s10
	v_mfma_f32_32x32x16_bf16 v[104:119], v[180:183], v[228:231], v[104:119]
	global_load_lds_dwordx4 v[76:77], off
	v_lshl_add_u64 v[76:77], v[76:77], 0, s[34:35]
	v_mfma_f32_32x32x16_bf16 v[128:143], v[180:183], v[252:255], v[128:143]
	s_mov_b32 m0, s11
	v_mfma_f32_32x32x16_bf16 v[196:211], v[184:187], v[228:231], v[196:211]
	global_load_lds_dwordx4 v[80:81], off
	v_lshl_add_u64 v[80:81], v[80:81], 0, s[34:35]
	v_mfma_f32_32x32x16_bf16 v[236:251], v[184:187], v[252:255], v[236:251]
	s_waitcnt vmcnt(6)
	s_barrier
	ds_read_b128 v[92:95], v84 offset:0
	ds_read_b128 v[96:99], v84 offset:4096
	ds_read_b128 v[188:191], v85 offset:32768
	ds_read_b128 v[192:195], v85 offset:36864
	ds_read_b128 v[100:103], v86 offset:0
	ds_read_b128 v[144:147], v86 offset:4096
	ds_read_b128 v[212:215], v87 offset:32768
	ds_read_b128 v[216:219], v87 offset:36864
	ds_read_b128 v[148:151], v88 offset:0
	ds_read_b128 v[152:155], v88 offset:4096
	ds_read_b128 v[220:223], v89 offset:32768
	ds_read_b128 v[224:227], v89 offset:36864
	ds_read_b128 v[180:183], v90 offset:0
	ds_read_b128 v[184:187], v90 offset:4096
	ds_read_b128 v[228:231], v91 offset:32768
	ds_read_b128 v[252:255], v91 offset:36864
	s_waitcnt lgkmcnt(12)
	v_mfma_f32_32x32x16_bf16 v[18:33], v[92:95], v[188:191], v[18:33]
	v_mfma_f32_32x32x16_bf16 v[50:65], v[92:95], v[192:195], v[50:65]
	v_mfma_f32_32x32x16_bf16 v[2:17], v[96:99], v[188:191], v[2:17]
	v_mfma_f32_32x32x16_bf16 v[34:49], v[96:99], v[192:195], v[34:49]
	s_waitcnt lgkmcnt(0)
	s_barrier
	s_mov_b32 m0, s1
	v_mfma_f32_32x32x16_bf16 v[18:33], v[100:103], v[212:215], v[18:33]
	global_load_lds_dwordx4 v[66:67], off
	v_mfma_f32_32x32x16_bf16 v[50:65], v[100:103], v[216:219], v[50:65]
	s_add_i32 m0, s1, 0x400
	v_mfma_f32_32x32x16_bf16 v[2:17], v[144:147], v[212:215], v[2:17]
	global_load_lds_dwordx4 v[70:71], off
	v_mfma_f32_32x32x16_bf16 v[34:49], v[144:147], v[216:219], v[34:49]
	s_add_i32 m0, s1, 0x800
	v_mfma_f32_32x32x16_bf16 v[18:33], v[148:151], v[220:223], v[18:33]
	global_load_lds_dwordx4 v[74:75], off
	v_mfma_f32_32x32x16_bf16 v[50:65], v[148:151], v[224:227], v[50:65]
	s_add_i32 m0, s1, 0xc00
	v_mfma_f32_32x32x16_bf16 v[2:17], v[152:155], v[220:223], v[2:17]
	global_load_lds_dwordx4 v[78:79], off
	v_mfma_f32_32x32x16_bf16 v[34:49], v[152:155], v[224:227], v[34:49]
	s_mov_b32 m0, s7
	v_mfma_f32_32x32x16_bf16 v[18:33], v[180:183], v[228:231], v[18:33]
	global_load_lds_dwordx4 v[68:69], off
	v_lshl_add_u64 v[68:69], v[68:69], 0, s[34:35]
	v_mfma_f32_32x32x16_bf16 v[50:65], v[180:183], v[252:255], v[50:65]
	s_mov_b32 m0, s14
	v_mfma_f32_32x32x16_bf16 v[2:17], v[184:187], v[228:231], v[2:17]
	global_load_lds_dwordx4 v[72:73], off
	v_lshl_add_u64 v[72:73], v[72:73], 0, s[34:35]
	v_mfma_f32_32x32x16_bf16 v[34:49], v[184:187], v[252:255], v[34:49]
	s_waitcnt vmcnt(6)
	s_barrier
	ds_read_b128 v[92:95], v84 offset:32768
	ds_read_b128 v[96:99], v84 offset:36864
	ds_read_b128 v[100:103], v86 offset:32768
	ds_read_b128 v[144:147], v86 offset:36864
	ds_read_b128 v[148:151], v88 offset:32768
	ds_read_b128 v[152:155], v88 offset:36864
	ds_read_b128 v[180:183], v90 offset:32768
	ds_read_b128 v[184:187], v90 offset:36864
	s_waitcnt lgkmcnt(6)
	v_mfma_f32_32x32x16_bf16 v[104:119], v[92:95], v[188:191], v[104:119]
	v_mfma_f32_32x32x16_bf16 v[128:143], v[92:95], v[192:195], v[128:143]
	v_mfma_f32_32x32x16_bf16 v[196:211], v[96:99], v[188:191], v[196:211]
	v_mfma_f32_32x32x16_bf16 v[236:251], v[96:99], v[192:195], v[236:251]
	s_waitcnt lgkmcnt(0)
	s_barrier
	s_mov_b32 m0, s6
	v_lshl_add_u64 v[82:83], v[66:67], 0, s[26:27]
	v_mfma_f32_32x32x16_bf16 v[104:119], v[100:103], v[212:215], v[104:119]
	global_load_lds_dwordx4 v[82:83], off
	v_lshl_add_u64 v[66:67], v[66:67], 0, s[34:35]
	v_mfma_f32_32x32x16_bf16 v[128:143], v[100:103], v[216:219], v[128:143]
	s_mov_b32 m0, s13
	v_lshl_add_u64 v[82:83], v[70:71], 0, s[26:27]
	v_mfma_f32_32x32x16_bf16 v[196:211], v[144:147], v[212:215], v[196:211]
	global_load_lds_dwordx4 v[82:83], off
	v_lshl_add_u64 v[70:71], v[70:71], 0, s[34:35]
	v_mfma_f32_32x32x16_bf16 v[236:251], v[144:147], v[216:219], v[236:251]
	s_mov_b32 m0, s15
	v_lshl_add_u64 v[82:83], v[74:75], 0, s[26:27]
	v_mfma_f32_32x32x16_bf16 v[104:119], v[148:151], v[220:223], v[104:119]
	global_load_lds_dwordx4 v[82:83], off
	v_lshl_add_u64 v[74:75], v[74:75], 0, s[34:35]
	v_mfma_f32_32x32x16_bf16 v[128:143], v[148:151], v[224:227], v[128:143]
	s_mov_b32 m0, s17
	v_lshl_add_u64 v[82:83], v[78:79], 0, s[26:27]
	v_mfma_f32_32x32x16_bf16 v[196:211], v[152:155], v[220:223], v[196:211]
	global_load_lds_dwordx4 v[82:83], off
	v_lshl_add_u64 v[78:79], v[78:79], 0, s[34:35]
	v_mfma_f32_32x32x16_bf16 v[236:251], v[152:155], v[224:227], v[236:251]
	s_mov_b32 m0, s16
	v_mfma_f32_32x32x16_bf16 v[104:119], v[180:183], v[228:231], v[104:119]
	global_load_lds_dwordx4 v[76:77], off
	v_lshl_add_u64 v[76:77], v[76:77], 0, s[34:35]
	v_mfma_f32_32x32x16_bf16 v[128:143], v[180:183], v[252:255], v[128:143]
	s_mov_b32 m0, s25
	v_mfma_f32_32x32x16_bf16 v[196:211], v[184:187], v[228:231], v[196:211]
	global_load_lds_dwordx4 v[80:81], off
	v_lshl_add_u64 v[80:81], v[80:81], 0, s[34:35]
	v_mfma_f32_32x32x16_bf16 v[236:251], v[184:187], v[252:255], v[236:251]
	s_waitcnt vmcnt(6)
	s_barrier
	s_add_i32 s12, s12, 2
	s_cmp_lt_u32 s12, 14
	s_cbranch_scc1 .Lg1_loop_w1
	ds_read_b128 v[92:95], v84 offset:0
	ds_read_b128 v[96:99], v84 offset:4096
	ds_read_b128 v[188:191], v85 offset:0
	ds_read_b128 v[192:195], v85 offset:4096
	ds_read_b128 v[100:103], v86 offset:0
	ds_read_b128 v[144:147], v86 offset:4096
	ds_read_b128 v[212:215], v87 offset:0
	ds_read_b128 v[216:219], v87 offset:4096
	ds_read_b128 v[148:151], v88 offset:0
	ds_read_b128 v[152:155], v88 offset:4096
	ds_read_b128 v[220:223], v89 offset:0
	ds_read_b128 v[224:227], v89 offset:4096
	ds_read_b128 v[180:183], v90 offset:0
	ds_read_b128 v[184:187], v90 offset:4096
	ds_read_b128 v[228:231], v91 offset:0
	ds_read_b128 v[252:255], v91 offset:4096
	s_waitcnt lgkmcnt(12)
	v_mfma_f32_32x32x16_bf16 v[18:33], v[92:95], v[188:191], v[18:33]
	v_mfma_f32_32x32x16_bf16 v[50:65], v[92:95], v[192:195], v[50:65]
	v_mfma_f32_32x32x16_bf16 v[2:17], v[96:99], v[188:191], v[2:17]
	v_mfma_f32_32x32x16_bf16 v[34:49], v[96:99], v[192:195], v[34:49]
	s_waitcnt lgkmcnt(0)
	s_barrier
	s_mov_b32 m0, s1
	v_mfma_f32_32x32x16_bf16 v[18:33], v[100:103], v[212:215], v[18:33]
	global_load_lds_dwordx4 v[66:67], off
	v_mfma_f32_32x32x16_bf16 v[50:65], v[100:103], v[216:219], v[50:65]
	s_add_i32 m0, s1, 0x400
	v_mfma_f32_32x32x16_bf16 v[2:17], v[144:147], v[212:215], v[2:17]
	global_load_lds_dwordx4 v[70:71], off
	v_mfma_f32_32x32x16_bf16 v[34:49], v[144:147], v[216:219], v[34:49]
	v_mfma_f32_32x32x16_bf16 v[18:33], v[148:151], v[220:223], v[18:33]
	v_mfma_f32_32x32x16_bf16 v[50:65], v[148:151], v[224:227], v[50:65]
	s_add_i32 m0, s1, 0x800
	v_mfma_f32_32x32x16_bf16 v[2:17], v[152:155], v[220:223], v[2:17]
	global_load_lds_dwordx4 v[74:75], off
	v_mfma_f32_32x32x16_bf16 v[34:49], v[152:155], v[224:227], v[34:49]
	s_add_i32 m0, s1, 0xc00
	v_mfma_f32_32x32x16_bf16 v[18:33], v[180:183], v[228:231], v[18:33]
	global_load_lds_dwordx4 v[78:79], off
	v_mfma_f32_32x32x16_bf16 v[50:65], v[180:183], v[252:255], v[50:65]
	v_mfma_f32_32x32x16_bf16 v[2:17], v[184:187], v[228:231], v[2:17]
	v_mfma_f32_32x32x16_bf16 v[34:49], v[184:187], v[252:255], v[34:49]
	s_waitcnt vmcnt(4)
	s_barrier
	ds_read_b128 v[92:95], v84 offset:32768
	ds_read_b128 v[96:99], v84 offset:36864
	ds_read_b128 v[100:103], v86 offset:32768
	ds_read_b128 v[144:147], v86 offset:36864
	ds_read_b128 v[148:151], v88 offset:32768
	ds_read_b128 v[152:155], v88 offset:36864
	ds_read_b128 v[180:183], v90 offset:32768
	ds_read_b128 v[184:187], v90 offset:36864
	s_waitcnt lgkmcnt(6)
	v_mfma_f32_32x32x16_bf16 v[104:119], v[92:95], v[188:191], v[104:119]
	v_mfma_f32_32x32x16_bf16 v[128:143], v[92:95], v[192:195], v[128:143]
	v_mfma_f32_32x32x16_bf16 v[196:211], v[96:99], v[188:191], v[196:211]
	v_mfma_f32_32x32x16_bf16 v[236:251], v[96:99], v[192:195], v[236:251]
	s_waitcnt lgkmcnt(0)
	s_barrier
	s_mov_b32 m0, s6
	v_lshl_add_u64 v[82:83], v[66:67], 0, s[26:27]
	v_mfma_f32_32x32x16_bf16 v[104:119], v[100:103], v[212:215], v[104:119]
	global_load_lds_dwordx4 v[82:83], off
	v_lshl_add_u64 v[66:67], v[66:67], 0, s[34:35]
	v_mfma_f32_32x32x16_bf16 v[128:143], v[100:103], v[216:219], v[128:143]
	s_mov_b32 m0, s13
	v_lshl_add_u64 v[82:83], v[70:71], 0, s[26:27]
	v_mfma_f32_32x32x16_bf16 v[196:211], v[144:147], v[212:215], v[196:211]
	global_load_lds_dwordx4 v[82:83], off
	v_lshl_add_u64 v[70:71], v[70:71], 0, s[34:35]
	v_mfma_f32_32x32x16_bf16 v[236:251], v[144:147], v[216:219], v[236:251]
	v_mfma_f32_32x32x16_bf16 v[104:119], v[148:151], v[220:223], v[104:119]
	v_mfma_f32_32x32x16_bf16 v[128:143], v[148:151], v[224:227], v[128:143]
	s_mov_b32 m0, s15
	v_lshl_add_u64 v[82:83], v[74:75], 0, s[26:27]
	v_mfma_f32_32x32x16_bf16 v[196:211], v[152:155], v[220:223], v[196:211]
	global_load_lds_dwordx4 v[82:83], off
	v_lshl_add_u64 v[74:75], v[74:75], 0, s[34:35]
	v_mfma_f32_32x32x16_bf16 v[236:251], v[152:155], v[224:227], v[236:251]
	s_mov_b32 m0, s17
	v_lshl_add_u64 v[82:83], v[78:79], 0, s[26:27]
	v_mfma_f32_32x32x16_bf16 v[104:119], v[180:183], v[228:231], v[104:119]
	global_load_lds_dwordx4 v[82:83], off
	v_lshl_add_u64 v[78:79], v[78:79], 0, s[34:35]
	v_mfma_f32_32x32x16_bf16 v[128:143], v[180:183], v[252:255], v[128:143]
	v_mfma_f32_32x32x16_bf16 v[196:211], v[184:187], v[228:231], v[196:211]
	v_mfma_f32_32x32x16_bf16 v[236:251], v[184:187], v[252:255], v[236:251]
	s_waitcnt vmcnt(4)
	s_barrier
	ds_read_b128 v[92:95], v84 offset:0
	ds_read_b128 v[96:99], v84 offset:4096
	ds_read_b128 v[188:191], v85 offset:32768
	ds_read_b128 v[192:195], v85 offset:36864
	ds_read_b128 v[100:103], v86 offset:0
	ds_read_b128 v[144:147], v86 offset:4096
	ds_read_b128 v[212:215], v87 offset:32768
	ds_read_b128 v[216:219], v87 offset:36864
	ds_read_b128 v[148:151], v88 offset:0
	ds_read_b128 v[152:155], v88 offset:4096
	ds_read_b128 v[220:223], v89 offset:32768
	ds_read_b128 v[224:227], v89 offset:36864
	ds_read_b128 v[180:183], v90 offset:0
	ds_read_b128 v[184:187], v90 offset:4096
	ds_read_b128 v[228:231], v91 offset:32768
	ds_read_b128 v[252:255], v91 offset:36864
	s_waitcnt lgkmcnt(12)
	v_mfma_f32_32x32x16_bf16 v[18:33], v[92:95], v[188:191], v[18:33]
	v_mfma_f32_32x32x16_bf16 v[50:65], v[92:95], v[192:195], v[50:65]
	v_mfma_f32_32x32x16_bf16 v[2:17], v[96:99], v[188:191], v[2:17]
	v_mfma_f32_32x32x16_bf16 v[34:49], v[96:99], v[192:195], v[34:49]
	s_waitcnt lgkmcnt(0)
	s_barrier
	v_mfma_f32_32x32x16_bf16 v[18:33], v[100:103], v[212:215], v[18:33]
	v_mfma_f32_32x32x16_bf16 v[50:65], v[100:103], v[216:219], v[50:65]
	v_mfma_f32_32x32x16_bf16 v[2:17], v[144:147], v[212:215], v[2:17]
	v_mfma_f32_32x32x16_bf16 v[34:49], v[144:147], v[216:219], v[34:49]
	v_mfma_f32_32x32x16_bf16 v[18:33], v[148:151], v[220:223], v[18:33]
	v_mfma_f32_32x32x16_bf16 v[50:65], v[148:151], v[224:227], v[50:65]
	v_mfma_f32_32x32x16_bf16 v[2:17], v[152:155], v[220:223], v[2:17]
	v_mfma_f32_32x32x16_bf16 v[34:49], v[152:155], v[224:227], v[34:49]
	v_mfma_f32_32x32x16_bf16 v[18:33], v[180:183], v[228:231], v[18:33]
	v_mfma_f32_32x32x16_bf16 v[50:65], v[180:183], v[252:255], v[50:65]
	v_mfma_f32_32x32x16_bf16 v[2:17], v[184:187], v[228:231], v[2:17]
	v_mfma_f32_32x32x16_bf16 v[34:49], v[184:187], v[252:255], v[34:49]
	s_waitcnt vmcnt(0)
	s_barrier
	ds_read_b128 v[92:95], v84 offset:32768
	ds_read_b128 v[96:99], v84 offset:36864
	ds_read_b128 v[100:103], v86 offset:32768
	ds_read_b128 v[144:147], v86 offset:36864
	ds_read_b128 v[148:151], v88 offset:32768
	ds_read_b128 v[152:155], v88 offset:36864
	ds_read_b128 v[180:183], v90 offset:32768
	ds_read_b128 v[184:187], v90 offset:36864
	s_waitcnt lgkmcnt(6)
	v_mfma_f32_32x32x16_bf16 v[104:119], v[92:95], v[188:191], v[104:119]
	v_mfma_f32_32x32x16_bf16 v[128:143], v[92:95], v[192:195], v[128:143]
	v_mfma_f32_32x32x16_bf16 v[196:211], v[96:99], v[188:191], v[196:211]
	v_mfma_f32_32x32x16_bf16 v[236:251], v[96:99], v[192:195], v[236:251]
	s_waitcnt lgkmcnt(0)
	s_barrier
	v_mfma_f32_32x32x16_bf16 v[104:119], v[100:103], v[212:215], v[104:119]
	v_mfma_f32_32x32x16_bf16 v[128:143], v[100:103], v[216:219], v[128:143]
	v_mfma_f32_32x32x16_bf16 v[196:211], v[144:147], v[212:215], v[196:211]
	v_mfma_f32_32x32x16_bf16 v[236:251], v[144:147], v[216:219], v[236:251]
	v_mfma_f32_32x32x16_bf16 v[104:119], v[148:151], v[220:223], v[104:119]
	v_mfma_f32_32x32x16_bf16 v[128:143], v[148:151], v[224:227], v[128:143]
	v_mfma_f32_32x32x16_bf16 v[196:211], v[152:155], v[220:223], v[196:211]
	v_mfma_f32_32x32x16_bf16 v[236:251], v[152:155], v[224:227], v[236:251]
	v_mfma_f32_32x32x16_bf16 v[104:119], v[180:183], v[228:231], v[104:119]
	v_mfma_f32_32x32x16_bf16 v[128:143], v[180:183], v[252:255], v[128:143]
	v_mfma_f32_32x32x16_bf16 v[196:211], v[184:187], v[228:231], v[196:211]
	v_mfma_f32_32x32x16_bf16 v[236:251], v[184:187], v[252:255], v[236:251]
	s_waitcnt vmcnt(0) lgkmcnt(0)
	s_barrier
	s_branch .LBB0_187
.Lg1_loop_w2:
	ds_read_b128 v[92:95], v84 offset:0
	ds_read_b128 v[96:99], v84 offset:4096
	ds_read_b128 v[188:191], v85 offset:0
	ds_read_b128 v[192:195], v85 offset:4096
	ds_read_b128 v[100:103], v86 offset:0
	ds_read_b128 v[144:147], v86 offset:4096
	ds_read_b128 v[212:215], v87 offset:0
	ds_read_b128 v[216:219], v87 offset:4096
	ds_read_b128 v[148:151], v88 offset:0
	ds_read_b128 v[152:155], v88 offset:4096
	ds_read_b128 v[220:223], v89 offset:0
	ds_read_b128 v[224:227], v89 offset:4096
	ds_read_b128 v[180:183], v90 offset:0
	ds_read_b128 v[184:187], v90 offset:4096
	ds_read_b128 v[228:231], v91 offset:0
	ds_read_b128 v[252:255], v91 offset:4096
	s_waitcnt lgkmcnt(12)
	v_mfma_f32_32x32x16_bf16 v[18:33], v[92:95], v[188:191], v[18:33]
	v_mfma_f32_32x32x16_bf16 v[50:65], v[92:95], v[192:195], v[50:65]
	v_mfma_f32_32x32x16_bf16 v[2:17], v[96:99], v[188:191], v[2:17]
	v_mfma_f32_32x32x16_bf16 v[34:49], v[96:99], v[192:195], v[34:49]
	s_waitcnt lgkmcnt(0)
	s_barrier
	s_mov_b32 m0, s1
	v_mfma_f32_32x32x16_bf16 v[18:33], v[100:103], v[212:215], v[18:33]
	global_load_lds_dwordx4 v[66:67], off
	v_mfma_f32_32x32x16_bf16 v[50:65], v[100:103], v[216:219], v[50:65]
	s_add_i32 m0, s1, 0x400
	v_mfma_f32_32x32x16_bf16 v[2:17], v[144:147], v[212:215], v[2:17]
	global_load_lds_dwordx4 v[70:71], off
	v_mfma_f32_32x32x16_bf16 v[34:49], v[144:147], v[216:219], v[34:49]
	v_mfma_f32_32x32x16_bf16 v[18:33], v[148:151], v[220:223], v[18:33]
	s_add_i32 m0, s1, 0x800
	v_mfma_f32_32x32x16_bf16 v[50:65], v[148:151], v[224:227], v[50:65]
	global_load_lds_dwordx4 v[74:75], off
	s_add_i32 m0, s1, 0xc00
	v_mfma_f32_32x32x16_bf16 v[2:17], v[152:155], v[220:223], v[2:17]
	global_load_lds_dwordx4 v[78:79], off
	v_mfma_f32_32x32x16_bf16 v[34:49], v[152:155], v[224:227], v[34:49]
	s_mov_b32 m0, s8
	v_mfma_f32_32x32x16_bf16 v[18:33], v[180:183], v[228:231], v[18:33]
	global_load_lds_dwordx4 v[68:69], off
	v_lshl_add_u64 v[68:69], v[68:69], 0, s[34:35]
	v_mfma_f32_32x32x16_bf16 v[50:65], v[180:183], v[252:255], v[50:65]
	v_mfma_f32_32x32x16_bf16 v[2:17], v[184:187], v[228:231], v[2:17]
	s_mov_b32 m0, s9
	v_mfma_f32_32x32x16_bf16 v[34:49], v[184:187], v[252:255], v[34:49]
	global_load_lds_dwordx4 v[72:73], off
	v_lshl_add_u64 v[72:73], v[72:73], 0, s[34:35]
	s_waitcnt vmcnt(6)
	s_barrier
	ds_read_b128 v[92:95], v84 offset:32768
	ds_read_b128 v[96:99], v84 offset:36864
	ds_read_b128 v[100:103], v86 offset:32768
	ds_read_b128 v[144:147], v86 offset:36864
	ds_read_b128 v[148:151], v88 offset:32768
	ds_read_b128 v[152:155], v88 offset:36864
	ds_read_b128 v[180:183], v90 offset:32768
	ds_read_b128 v[184:187], v90 offset:36864
	s_waitcnt lgkmcnt(6)
	v_mfma_f32_32x32x16_bf16 v[104:119], v[92:95], v[188:191], v[104:119]
	v_mfma_f32_32x32x16_bf16 v[128:143], v[92:95], v[192:195], v[128:143]
	v_mfma_f32_32x32x16_bf16 v[196:211], v[96:99], v[188:191], v[196:211]
	v_mfma_f32_32x32x16_bf16 v[236:251], v[96:99], v[192:195], v[236:251]
	s_waitcnt lgkmcnt(0)
	s_barrier
	s_mov_b32 m0, s6
	v_lshl_add_u64 v[82:83], v[66:67], 0, s[26:27]
	v_mfma_f32_32x32x16_bf16 v[104:119], v[100:103], v[212:215], v[104:119]
	global_load_lds_dwordx4 v[82:83], off
	v_lshl_add_u64 v[66:67], v[66:67], 0, s[34:35]
	v_mfma_f32_32x32x16_bf16 v[128:143], v[100:103], v[216:219], v[128:143]
	s_mov_b32 m0, s13
	v_lshl_add_u64 v[82:83], v[70:71], 0, s[26:27]
	v_mfma_f32_32x32x16_bf16 v[196:211], v[144:147], v[212:215], v[196:211]
	global_load_lds_dwordx4 v[82:83], off
	v_lshl_add_u64 v[70:71], v[70:71], 0, s[34:35]
	v_mfma_f32_32x32x16_bf16 v[236:251], v[144:147], v[216:219], v[236:251]
	v_mfma_f32_32x32x16_bf16 v[104:119], v[148:151], v[220:223], v[104:119]
	s_mov_b32 m0, s15
	v_lshl_add_u64 v[82:83], v[74:75], 0, s[26:27]
	v_mfma_f32_32x32x16_bf16 v[128:143], v[148:151], v[224:227], v[128:143]
	global_load_lds_dwordx4 v[82:83], off
	v_lshl_add_u64 v[74:75], v[74:75], 0, s[34:35]
	s_mov_b32 m0, s17
	v_lshl_add_u64 v[82:83], v[78:79], 0, s[26:27]
	v_mfma_f32_32x32x16_bf16 v[196:211], v[152:155], v[220:223], v[196:211]
	global_load_lds_dwordx4 v[82:83], off
	v_lshl_add_u64 v[78:79], v[78:79], 0, s[34:35]
	v_mfma_f32_32x32x16_bf16 v[236:251], v[152:155], v[224:227], v[236:251]
	s_mov_b32 m0, s10
	v_mfma_f32_32x32x16_bf16 v[104:119], v[180:183], v[228:231], v[104:119]
	global_load_lds_dwordx4 v[76:77], off
	v_lshl_add_u64 v[76:77], v[76:77], 0, s[34:35]
	v_mfma_f32_32x32x16_bf16 v[128:143], v[180:183], v[252:255], v[128:143]
	v_mfma_f32_32x32x16_bf16 v[196:211], v[184:187], v[228:231], v[196:211]
	s_mov_b32 m0, s11
	v_mfma_f32_32x32x16_bf16 v[236:251], v[184:187], v[252:255], v[236:251]
	global_load_lds_dwordx4 v[80:81], off
	v_lshl_add_u64 v[80:81], v[80:81], 0, s[34:35]
	s_waitcnt vmcnt(6)
	s_barrier
	ds_read_b128 v[92:95], v84 offset:0
	ds_read_b128 v[96:99], v84 offset:4096
	ds_read_b128 v[188:191], v85 offset:32768
	ds_read_b128 v[192:195], v85 offset:36864
	ds_read_b128 v[100:103], v86 offset:0
	ds_read_b128 v[144:147], v86 offset:4096
	ds_read_b128 v[212:215], v87 offset:32768
	ds_read_b128 v[216:219], v87 offset:36864
	ds_read_b128 v[148:151], v88 offset:0
	ds_read_b128 v[152:155], v88 offset:4096
	ds_read_b128 v[220:223], v89 offset:32768
	ds_read_b128 v[224:227], v89 offset:36864
	ds_read_b128 v[180:183], v90 offset:0
	ds_read_b128 v[184:187], v90 offset:4096
	ds_read_b128 v[228:231], v91 offset:32768
	ds_read_b128 v[252:255], v91 offset:36864
	s_waitcnt lgkmcnt(12)
	v_mfma_f32_32x32x16_bf16 v[18:33], v[92:95], v[188:191], v[18:33]
	v_mfma_f32_32x32x16_bf16 v[50:65], v[92:95], v[192:195], v[50:65]
	v_mfma_f32_32x32x16_bf16 v[2:17], v[96:99], v[188:191], v[2:17]
	v_mfma_f32_32x32x16_bf16 v[34:49], v[96:99], v[192:195], v[34:49]
	s_waitcnt lgkmcnt(0)
	s_barrier
	s_mov_b32 m0, s1
	v_mfma_f32_32x32x16_bf16 v[18:33], v[100:103], v[212:215], v[18:33]
	global_load_lds_dwordx4 v[66:67], off
	v_mfma_f32_32x32x16_bf16 v[50:65], v[100:103], v[216:219], v[50:65]
	s_add_i32 m0, s1, 0x400
	v_mfma_f32_32x32x16_bf16 v[2:17], v[144:147], v[212:215], v[2:17]
	global_load_lds_dwordx4 v[70:71], off
	v_mfma_f32_32x32x16_bf16 v[34:49], v[144:147], v[216:219], v[34:49]
	v_mfma_f32_32x32x16_bf16 v[18:33], v[148:151], v[220:223], v[18:33]
	s_add_i32 m0, s1, 0x800
	v_mfma_f32_32x32x16_bf16 v[50:65], v[148:151], v[224:227], v[50:65]
	global_load_lds_dwordx4 v[74:75], off
	s_add_i32 m0, s1, 0xc00
	v_mfma_f32_32x32x16_bf16 v[2:17], v[152:155], v[220:223], v[2:17]
	global_load_lds_dwordx4 v[78:79], off
	v_mfma_f32_32x32x16_bf16 v[34:49], v[152:155], v[224:227], v[34:49]
	s_mov_b32 m0, s7
	v_mfma_f32_32x32x16_bf16 v[18:33], v[180:183], v[228:231], v[18:33]
	global_load_lds_dwordx4 v[68:69], off
	v_lshl_add_u64 v[68:69], v[68:69], 0, s[34:35]
	v_mfma_f32_32x32x16_bf16 v[50:65], v[180:183], v[252:255], v[50:65]
	v_mfma_f32_32x32x16_bf16 v[2:17], v[184:187], v[228:231], v[2:17]
	s_mov_b32 m0, s14
	v_mfma_f32_32x32x16_bf16 v[34:49], v[184:187], v[252:255], v[34:49]
	global_load_lds_dwordx4 v[72:73], off
	v_lshl_add_u64 v[72:73], v[72:73], 0, s[34:35]
	s_waitcnt vmcnt(6)
	s_barrier
	ds_read_b128 v[92:95], v84 offset:32768
	ds_read_b128 v[96:99], v84 offset:36864
	ds_read_b128 v[100:103], v86 offset:32768
	ds_read_b128 v[144:147], v86 offset:36864
	ds_read_b128 v[148:151], v88 offset:32768
	ds_read_b128 v[152:155], v88 offset:36864
	ds_read_b128 v[180:183], v90 offset:32768
	ds_read_b128 v[184:187], v90 offset:36864
	s_waitcnt lgkmcnt(6)
	v_mfma_f32_32x32x16_bf16 v[104:119], v[92:95], v[188:191], v[104:119]
	v_mfma_f32_32x32x16_bf16 v[128:143], v[92:95], v[192:195], v[128:143]
	v_mfma_f32_32x32x16_bf16 v[196:211], v[96:99], v[188:191], v[196:211]
	v_mfma_f32_32x32x16_bf16 v[236:251], v[96:99], v[192:195], v[236:251]
	s_waitcnt lgkmcnt(0)
	s_barrier
	s_mov_b32 m0, s6
	v_lshl_add_u64 v[82:83], v[66:67], 0, s[26:27]
	v_mfma_f32_32x32x16_bf16 v[104:119], v[100:103], v[212:215], v[104:119]
	global_load_lds_dwordx4 v[82:83], off
	v_lshl_add_u64 v[66:67], v[66:67], 0, s[34:35]
	v_mfma_f32_32x32x16_bf16 v[128:143], v[100:103], v[216:219], v[128:143]
	s_mov_b32 m0, s13
	v_lshl_add_u64 v[82:83], v[70:71], 0, s[26:27]
	v_mfma_f32_32x32x16_bf16 v[196:211], v[144:147], v[212:215], v[196:211]
	global_load_lds_dwordx4 v[82:83], off
	v_lshl_add_u64 v[70:71], v[70:71], 0, s[34:35]
	v_mfma_f32_32x32x16_bf16 v[236:251], v[144:147], v[216:219], v[236:251]
	v_mfma_f32_32x32x16_bf16 v[104:119], v[148:151], v[220:223], v[104:119]
	s_mov_b32 m0, s15
	v_lshl_add_u64 v[82:83], v[74:75], 0, s[26:27]
	v_mfma_f32_32x32x16_bf16 v[128:143], v[148:151], v[224:227], v[128:143]
	global_load_lds_dwordx4 v[82:83], off
	v_lshl_add_u64 v[74:75], v[74:75], 0, s[34:35]
	s_mov_b32 m0, s17
	v_lshl_add_u64 v[82:83], v[78:79], 0, s[26:27]
	v_mfma_f32_32x32x16_bf16 v[196:211], v[152:155], v[220:223], v[196:211]
	global_load_lds_dwordx4 v[82:83], off
	v_lshl_add_u64 v[78:79], v[78:79], 0, s[34:35]
	v_mfma_f32_32x32x16_bf16 v[236:251], v[152:155], v[224:227], v[236:251]
	s_mov_b32 m0, s16
	v_mfma_f32_32x32x16_bf16 v[104:119], v[180:183], v[228:231], v[104:119]
	global_load_lds_dwordx4 v[76:77], off
	v_lshl_add_u64 v[76:77], v[76:77], 0, s[34:35]
	v_mfma_f32_32x32x16_bf16 v[128:143], v[180:183], v[252:255], v[128:143]
	v_mfma_f32_32x32x16_bf16 v[196:211], v[184:187], v[228:231], v[196:211]
	s_mov_b32 m0, s25
	v_mfma_f32_32x32x16_bf16 v[236:251], v[184:187], v[252:255], v[236:251]
	global_load_lds_dwordx4 v[80:81], off
	v_lshl_add_u64 v[80:81], v[80:81], 0, s[34:35]
	s_waitcnt vmcnt(6)
	s_barrier
	s_add_i32 s12, s12, 2
	s_cmp_lt_u32 s12, 14
	s_cbranch_scc1 .Lg1_loop_w2
	ds_read_b128 v[92:95], v84 offset:0
	ds_read_b128 v[96:99], v84 offset:4096
	ds_read_b128 v[188:191], v85 offset:0
	ds_read_b128 v[192:195], v85 offset:4096
	ds_read_b128 v[100:103], v86 offset:0
	ds_read_b128 v[144:147], v86 offset:4096
	ds_read_b128 v[212:215], v87 offset:0
	ds_read_b128 v[216:219], v87 offset:4096
	ds_read_b128 v[148:151], v88 offset:0
	ds_read_b128 v[152:155], v88 offset:4096
	ds_read_b128 v[220:223], v89 offset:0
	ds_read_b128 v[224:227], v89 offset:4096
	ds_read_b128 v[180:183], v90 offset:0
	ds_read_b128 v[184:187], v90 offset:4096
	ds_read_b128 v[228:231], v91 offset:0
	ds_read_b128 v[252:255], v91 offset:4096
	s_waitcnt lgkmcnt(12)
	v_mfma_f32_32x32x16_bf16 v[18:33], v[92:95], v[188:191], v[18:33]
	v_mfma_f32_32x32x16_bf16 v[50:65], v[92:95], v[192:195], v[50:65]
	v_mfma_f32_32x32x16_bf16 v[2:17], v[96:99], v[188:191], v[2:17]
	v_mfma_f32_32x32x16_bf16 v[34:49], v[96:99], v[192:195], v[34:49]
	s_waitcnt lgkmcnt(0)
	s_barrier
	s_mov_b32 m0, s1
	v_mfma_f32_32x32x16_bf16 v[18:33], v[100:103], v[212:215], v[18:33]
	global_load_lds_dwordx4 v[66:67], off
	v_mfma_f32_32x32x16_bf16 v[50:65], v[100:103], v[216:219], v[50:65]
	s_add_i32 m0, s1, 0x400
	v_mfma_f32_32x32x16_bf16 v[2:17], v[144:147], v[212:215], v[2:17]
	global_load_lds_dwordx4 v[70:71], off
	v_mfma_f32_32x32x16_bf16 v[34:49], v[144:147], v[216:219], v[34:49]
	v_mfma_f32_32x32x16_bf16 v[18:33], v[148:151], v[220:223], v[18:33]
	v_mfma_f32_32x32x16_bf16 v[50:65], v[148:151], v[224:227], v[50:65]
	s_add_i32 m0, s1, 0x800
	v_mfma_f32_32x32x16_bf16 v[2:17], v[152:155], v[220:223], v[2:17]
	global_load_lds_dwordx4 v[74:75], off
	v_mfma_f32_32x32x16_bf16 v[34:49], v[152:155], v[224:227], v[34:49]
	s_add_i32 m0, s1, 0xc00
	v_mfma_f32_32x32x16_bf16 v[18:33], v[180:183], v[228:231], v[18:33]
	global_load_lds_dwordx4 v[78:79], off
	v_mfma_f32_32x32x16_bf16 v[50:65], v[180:183], v[252:255], v[50:65]
	v_mfma_f32_32x32x16_bf16 v[2:17], v[184:187], v[228:231], v[2:17]
	v_mfma_f32_32x32x16_bf16 v[34:49], v[184:187], v[252:255], v[34:49]
	s_waitcnt vmcnt(4)
	s_barrier
	ds_read_b128 v[92:95], v84 offset:32768
	ds_read_b128 v[96:99], v84 offset:36864
	ds_read_b128 v[100:103], v86 offset:32768
	ds_read_b128 v[144:147], v86 offset:36864
	ds_read_b128 v[148:151], v88 offset:32768
	ds_read_b128 v[152:155], v88 offset:36864
	ds_read_b128 v[180:183], v90 offset:32768
	ds_read_b128 v[184:187], v90 offset:36864
	s_waitcnt lgkmcnt(6)
	v_mfma_f32_32x32x16_bf16 v[104:119], v[92:95], v[188:191], v[104:119]
	v_mfma_f32_32x32x16_bf16 v[128:143], v[92:95], v[192:195], v[128:143]
	v_mfma_f32_32x32x16_bf16 v[196:211], v[96:99], v[188:191], v[196:211]
	v_mfma_f32_32x32x16_bf16 v[236:251], v[96:99], v[192:195], v[236:251]
	s_waitcnt lgkmcnt(0)
	s_barrier
	s_mov_b32 m0, s6
	v_lshl_add_u64 v[82:83], v[66:67], 0, s[26:27]
	v_mfma_f32_32x32x16_bf16 v[104:119], v[100:103], v[212:215], v[104:119]
	global_load_lds_dwordx4 v[82:83], off
	v_lshl_add_u64 v[66:67], v[66:67], 0, s[34:35]
	v_mfma_f32_32x32x16_bf16 v[128:143], v[100:103], v[216:219], v[128:143]
	s_mov_b32 m0, s13
	v_lshl_add_u64 v[82:83], v[70:71], 0, s[26:27]
	v_mfma_f32_32x32x16_bf16 v[196:211], v[144:147], v[212:215], v[196:211]
	global_load_lds_dwordx4 v[82:83], off
	v_lshl_add_u64 v[70:71], v[70:71], 0, s[34:35]
	v_mfma_f32_32x32x16_bf16 v[236:251], v[144:147], v[216:219], v[236:251]
	v_mfma_f32_32x32x16_bf16 v[104:119], v[148:151], v[220:223], v[104:119]
	v_mfma_f32_32x32x16_bf16 v[128:143], v[148:151], v[224:227], v[128:143]
	s_mov_b32 m0, s15
	v_lshl_add_u64 v[82:83], v[74:75], 0, s[26:27]
	v_mfma_f32_32x32x16_bf16 v[196:211], v[152:155], v[220:223], v[196:211]
	global_load_lds_dwordx4 v[82:83], off
	v_lshl_add_u64 v[74:75], v[74:75], 0, s[34:35]
	v_mfma_f32_32x32x16_bf16 v[236:251], v[152:155], v[224:227], v[236:251]
	s_mov_b32 m0, s17
	v_lshl_add_u64 v[82:83], v[78:79], 0, s[26:27]
	v_mfma_f32_32x32x16_bf16 v[104:119], v[180:183], v[228:231], v[104:119]
	global_load_lds_dwordx4 v[82:83], off
	v_lshl_add_u64 v[78:79], v[78:79], 0, s[34:35]
	v_mfma_f32_32x32x16_bf16 v[128:143], v[180:183], v[252:255], v[128:143]
	v_mfma_f32_32x32x16_bf16 v[196:211], v[184:187], v[228:231], v[196:211]
	v_mfma_f32_32x32x16_bf16 v[236:251], v[184:187], v[252:255], v[236:251]
	s_waitcnt vmcnt(4)
	s_barrier
	ds_read_b128 v[92:95], v84 offset:0
	ds_read_b128 v[96:99], v84 offset:4096
	ds_read_b128 v[188:191], v85 offset:32768
	ds_read_b128 v[192:195], v85 offset:36864
	ds_read_b128 v[100:103], v86 offset:0
	ds_read_b128 v[144:147], v86 offset:4096
	ds_read_b128 v[212:215], v87 offset:32768
	ds_read_b128 v[216:219], v87 offset:36864
	ds_read_b128 v[148:151], v88 offset:0
	ds_read_b128 v[152:155], v88 offset:4096
	ds_read_b128 v[220:223], v89 offset:32768
	ds_read_b128 v[224:227], v89 offset:36864
	ds_read_b128 v[180:183], v90 offset:0
	ds_read_b128 v[184:187], v90 offset:4096
	ds_read_b128 v[228:231], v91 offset:32768
	ds_read_b128 v[252:255], v91 offset:36864
	s_waitcnt lgkmcnt(12)
	v_mfma_f32_32x32x16_bf16 v[18:33], v[92:95], v[188:191], v[18:33]
	v_mfma_f32_32x32x16_bf16 v[50:65], v[92:95], v[192:195], v[50:65]
	v_mfma_f32_32x32x16_bf16 v[2:17], v[96:99], v[188:191], v[2:17]
	v_mfma_f32_32x32x16_bf16 v[34:49], v[96:99], v[192:195], v[34:49]
	s_waitcnt lgkmcnt(0)
	s_barrier
	v_mfma_f32_32x32x16_bf16 v[18:33], v[100:103], v[212:215], v[18:33]
	v_mfma_f32_32x32x16_bf16 v[50:65], v[100:103], v[216:219], v[50:65]
	v_mfma_f32_32x32x16_bf16 v[2:17], v[144:147], v[212:215], v[2:17]
	v_mfma_f32_32x32x16_bf16 v[34:49], v[144:147], v[216:219], v[34:49]
	v_mfma_f32_32x32x16_bf16 v[18:33], v[148:151], v[220:223], v[18:33]
	v_mfma_f32_32x32x16_bf16 v[50:65], v[148:151], v[224:227], v[50:65]
	v_mfma_f32_32x32x16_bf16 v[2:17], v[152:155], v[220:223], v[2:17]
	v_mfma_f32_32x32x16_bf16 v[34:49], v[152:155], v[224:227], v[34:49]
	v_mfma_f32_32x32x16_bf16 v[18:33], v[180:183], v[228:231], v[18:33]
	v_mfma_f32_32x32x16_bf16 v[50:65], v[180:183], v[252:255], v[50:65]
	v_mfma_f32_32x32x16_bf16 v[2:17], v[184:187], v[228:231], v[2:17]
	v_mfma_f32_32x32x16_bf16 v[34:49], v[184:187], v[252:255], v[34:49]
	s_waitcnt vmcnt(0)
	s_barrier
	ds_read_b128 v[92:95], v84 offset:32768
	ds_read_b128 v[96:99], v84 offset:36864
	ds_read_b128 v[100:103], v86 offset:32768
	ds_read_b128 v[144:147], v86 offset:36864
	ds_read_b128 v[148:151], v88 offset:32768
	ds_read_b128 v[152:155], v88 offset:36864
	ds_read_b128 v[180:183], v90 offset:32768
	ds_read_b128 v[184:187], v90 offset:36864
	s_waitcnt lgkmcnt(6)
	v_mfma_f32_32x32x16_bf16 v[104:119], v[92:95], v[188:191], v[104:119]
	v_mfma_f32_32x32x16_bf16 v[128:143], v[92:95], v[192:195], v[128:143]
	v_mfma_f32_32x32x16_bf16 v[196:211], v[96:99], v[188:191], v[196:211]
	v_mfma_f32_32x32x16_bf16 v[236:251], v[96:99], v[192:195], v[236:251]
	s_waitcnt lgkmcnt(0)
	s_barrier
	v_mfma_f32_32x32x16_bf16 v[104:119], v[100:103], v[212:215], v[104:119]
	v_mfma_f32_32x32x16_bf16 v[128:143], v[100:103], v[216:219], v[128:143]
	v_mfma_f32_32x32x16_bf16 v[196:211], v[144:147], v[212:215], v[196:211]
	v_mfma_f32_32x32x16_bf16 v[236:251], v[144:147], v[216:219], v[236:251]
	v_mfma_f32_32x32x16_bf16 v[104:119], v[148:151], v[220:223], v[104:119]
	v_mfma_f32_32x32x16_bf16 v[128:143], v[148:151], v[224:227], v[128:143]
	v_mfma_f32_32x32x16_bf16 v[196:211], v[152:155], v[220:223], v[196:211]
	v_mfma_f32_32x32x16_bf16 v[236:251], v[152:155], v[224:227], v[236:251]
	v_mfma_f32_32x32x16_bf16 v[104:119], v[180:183], v[228:231], v[104:119]
	v_mfma_f32_32x32x16_bf16 v[128:143], v[180:183], v[252:255], v[128:143]
	v_mfma_f32_32x32x16_bf16 v[196:211], v[184:187], v[228:231], v[196:211]
	v_mfma_f32_32x32x16_bf16 v[236:251], v[184:187], v[252:255], v[236:251]
	s_waitcnt vmcnt(0) lgkmcnt(0)
	s_barrier
	s_branch .LBB0_187
.Lg1_loop_w3:
	ds_read_b128 v[92:95], v84 offset:0
	ds_read_b128 v[96:99], v84 offset:4096
	ds_read_b128 v[188:191], v85 offset:0
	ds_read_b128 v[192:195], v85 offset:4096
	ds_read_b128 v[100:103], v86 offset:0
	ds_read_b128 v[144:147], v86 offset:4096
	ds_read_b128 v[212:215], v87 offset:0
	ds_read_b128 v[216:219], v87 offset:4096
	ds_read_b128 v[148:151], v88 offset:0
	ds_read_b128 v[152:155], v88 offset:4096
	ds_read_b128 v[220:223], v89 offset:0
	ds_read_b128 v[224:227], v89 offset:4096
	ds_read_b128 v[180:183], v90 offset:0
	ds_read_b128 v[184:187], v90 offset:4096
	ds_read_b128 v[228:231], v91 offset:0
	ds_read_b128 v[252:255], v91 offset:4096
	s_waitcnt lgkmcnt(12)
	v_mfma_f32_32x32x16_bf16 v[18:33], v[92:95], v[188:191], v[18:33]
	v_mfma_f32_32x32x16_bf16 v[50:65], v[92:95], v[192:195], v[50:65]
	v_mfma_f32_32x32x16_bf16 v[2:17], v[96:99], v[188:191], v[2:17]
	v_mfma_f32_32x32x16_bf16 v[34:49], v[96:99], v[192:195], v[34:49]
	s_waitcnt lgkmcnt(0)
	s_barrier
	v_mfma_f32_32x32x16_bf16 v[18:33], v[100:103], v[212:215], v[18:33]
	s_mov_b32 m0, s1
	v_mfma_f32_32x32x16_bf16 v[50:65], v[100:103], v[216:219], v[50:65]
	global_load_lds_dwordx4 v[66:67], off
	v_mfma_f32_32x32x16_bf16 v[2:17], v[144:147], v[212:215], v[2:17]
	s_add_i32 m0, s1, 0x400
	v_mfma_f32_32x32x16_bf16 v[34:49], v[144:147], v[216:219], v[34:49]
	global_load_lds_dwordx4 v[70:71], off
	v_mfma_f32_32x32x16_bf16 v[18:33], v[148:151], v[220:223], v[18:33]
	s_add_i32 m0, s1, 0x800
	v_mfma_f32_32x32x16_bf16 v[50:65], v[148:151], v[224:227], v[50:65]
	global_load_lds_dwordx4 v[74:75], off
	v_mfma_f32_32x32x16_bf16 v[2:17], v[152:155], v[220:223], v[2:17]
	s_add_i32 m0, s1, 0xc00
	v_mfma_f32_32x32x16_bf16 v[34:49], v[152:155], v[224:227], v[34:49]
	global_load_lds_dwordx4 v[78:79], off
	v_mfma_f32_32x32x16_bf16 v[18:33], v[180:183], v[228:231], v[18:33]
	s_mov_b32 m0, s8
	v_mfma_f32_32x32x16_bf16 v[50:65], v[180:183], v[252:255], v[50:65]
	global_load_lds_dwordx4 v[68:69], off
	v_lshl_add_u64 v[68:69], v[68:69], 0, s[34:35]
	v_mfma_f32_32x32x16_bf16 v[2:17], v[184:187], v[228:231], v[2:17]
	s_mov_b32 m0, s9
	v_mfma_f32_32x32x16_bf16 v[34:49], v[184:187], v[252:255], v[34:49]
	global_load_lds_dwordx4 v[72:73], off
	v_lshl_add_u64 v[72:73], v[72:73], 0, s[34:35]
	s_waitcnt vmcnt(6)
	s_barrier
	ds_read_b128 v[92:95], v84 offset:32768
	ds_read_b128 v[96:99], v84 offset:36864
	ds_read_b128 v[100:103], v86 offset:32768
	ds_read_b128 v[144:147], v86 offset:36864
	ds_read_b128 v[148:151], v88 offset:32768
	ds_read_b128 v[152:155], v88 offset:36864
	ds_read_b128 v[180:183], v90 offset:32768
	ds_read_b128 v[184:187], v90 offset:36864
	s_waitcnt lgkmcnt(6)
	v_mfma_f32_32x32x16_bf16 v[104:119], v[92:95], v[188:191], v[104:119]
	v_mfma_f32_32x32x16_bf16 v[128:143], v[92:95], v[192:195], v[128:143]
	v_mfma_f32_32x32x16_bf16 v[196:211], v[96:99], v[188:191], v[196:211]
	v_mfma_f32_32x32x16_bf16 v[236:251], v[96:99], v[192:195], v[236:251]
	s_waitcnt lgkmcnt(0)
	s_barrier
	v_mfma_f32_32x32x16_bf16 v[104:119], v[100:103], v[212:215], v[104:119]
	s_mov_b32 m0, s6
	v_lshl_add_u64 v[82:83], v[66:67], 0, s[26:27]
	v_mfma_f32_32x32x16_bf16 v[128:143], v[100:103], v[216:219], v[128:143]
	global_load_lds_dwordx4 v[82:83], off
	v_lshl_add_u64 v[66:67], v[66:67], 0, s[34:35]
	v_mfma_f32_32x32x16_bf16 v[196:211], v[144:147], v[212:215], v[196:211]
	s_mov_b32 m0, s13
	v_lshl_add_u64 v[82:83], v[70:71], 0, s[26:27]
	v_mfma_f32_32x32x16_bf16 v[236:251], v[144:147], v[216:219], v[236:251]
	global_load_lds_dwordx4 v[82:83], off
	v_lshl_add_u64 v[70:71], v[70:71], 0, s[34:35]
	v_mfma_f32_32x32x16_bf16 v[104:119], v[148:151], v[220:223], v[104:119]
	s_mov_b32 m0, s15
	v_lshl_add_u64 v[82:83], v[74:75], 0, s[26:27]
	v_mfma_f32_32x32x16_bf16 v[128:143], v[148:151], v[224:227], v[128:143]
	global_load_lds_dwordx4 v[82:83], off
	v_lshl_add_u64 v[74:75], v[74:75], 0, s[34:35]
	v_mfma_f32_32x32x16_bf16 v[196:211], v[152:155], v[220:223], v[196:211]
	s_mov_b32 m0, s17
	v_lshl_add_u64 v[82:83], v[78:79], 0, s[26:27]
	v_mfma_f32_32x32x16_bf16 v[236:251], v[152:155], v[224:227], v[236:251]
	global_load_lds_dwordx4 v[82:83], off
	v_lshl_add_u64 v[78:79], v[78:79], 0, s[34:35]
	v_mfma_f32_32x32x16_bf16 v[104:119], v[180:183], v[228:231], v[104:119]
	s_mov_b32 m0, s10
	v_mfma_f32_32x32x16_bf16 v[128:143], v[180:183], v[252:255], v[128:143]
	global_load_lds_dwordx4 v[76:77], off
	v_lshl_add_u64 v[76:77], v[76:77], 0, s[34:35]
	v_mfma_f32_32x32x16_bf16 v[196:211], v[184:187], v[228:231], v[196:211]
	s_mov_b32 m0, s11
	v_mfma_f32_32x32x16_bf16 v[236:251], v[184:187], v[252:255], v[236:251]
	global_load_lds_dwordx4 v[80:81], off
	v_lshl_add_u64 v[80:81], v[80:81], 0, s[34:35]
	s_waitcnt vmcnt(6)
	s_barrier
	ds_read_b128 v[92:95], v84 offset:0
	ds_read_b128 v[96:99], v84 offset:4096
	ds_read_b128 v[188:191], v85 offset:32768
	ds_read_b128 v[192:195], v85 offset:36864
	ds_read_b128 v[100:103], v86 offset:0
	ds_read_b128 v[144:147], v86 offset:4096
	ds_read_b128 v[212:215], v87 offset:32768
	ds_read_b128 v[216:219], v87 offset:36864
	ds_read_b128 v[148:151], v88 offset:0
	ds_read_b128 v[152:155], v88 offset:4096
	ds_read_b128 v[220:223], v89 offset:32768
	ds_read_b128 v[224:227], v89 offset:36864
	ds_read_b128 v[180:183], v90 offset:0
	ds_read_b128 v[184:187], v90 offset:4096
	ds_read_b128 v[228:231], v91 offset:32768
	ds_read_b128 v[252:255], v91 offset:36864
	s_waitcnt lgkmcnt(12)
	v_mfma_f32_32x32x16_bf16 v[18:33], v[92:95], v[188:191], v[18:33]
	v_mfma_f32_32x32x16_bf16 v[50:65], v[92:95], v[192:195], v[50:65]
	v_mfma_f32_32x32x16_bf16 v[2:17], v[96:99], v[188:191], v[2:17]
	v_mfma_f32_32x32x16_bf16 v[34:49], v[96:99], v[192:195], v[34:49]
	s_waitcnt lgkmcnt(0)
	s_barrier
	v_mfma_f32_32x32x16_bf16 v[18:33], v[100:103], v[212:215], v[18:33]
	s_mov_b32 m0, s1
	v_mfma_f32_32x32x16_bf16 v[50:65], v[100:103], v[216:219], v[50:65]
	global_load_lds_dwordx4 v[66:67], off
	v_mfma_f32_32x32x16_bf16 v[2:17], v[144:147], v[212:215], v[2:17]
	s_add_i32 m0, s1, 0x400
	v_mfma_f32_32x32x16_bf16 v[34:49], v[144:147], v[216:219], v[34:49]
	global_load_lds_dwordx4 v[70:71], off
	v_mfma_f32_32x32x16_bf16 v[18:33], v[148:151], v[220:223], v[18:33]
	s_add_i32 m0, s1, 0x800
	v_mfma_f32_32x32x16_bf16 v[50:65], v[148:151], v[224:227], v[50:65]
	global_load_lds_dwordx4 v[74:75], off
	v_mfma_f32_32x32x16_bf16 v[2:17], v[152:155], v[220:223], v[2:17]
	s_add_i32 m0, s1, 0xc00
	v_mfma_f32_32x32x16_bf16 v[34:49], v[152:155], v[224:227], v[34:49]
	global_load_lds_dwordx4 v[78:79], off
	v_mfma_f32_32x32x16_bf16 v[18:33], v[180:183], v[228:231], v[18:33]
	s_mov_b32 m0, s7
	v_mfma_f32_32x32x16_bf16 v[50:65], v[180:183], v[252:255], v[50:65]
	global_load_lds_dwordx4 v[68:69], off
	v_lshl_add_u64 v[68:69], v[68:69], 0, s[34:35]
	v_mfma_f32_32x32x16_bf16 v[2:17], v[184:187], v[228:231], v[2:17]
	s_mov_b32 m0, s14
	v_mfma_f32_32x32x16_bf16 v[34:49], v[184:187], v[252:255], v[34:49]
	global_load_lds_dwordx4 v[72:73], off
	v_lshl_add_u64 v[72:73], v[72:73], 0, s[34:35]
	s_waitcnt vmcnt(6)
	s_barrier
	ds_read_b128 v[92:95], v84 offset:32768
	ds_read_b128 v[96:99], v84 offset:36864
	ds_read_b128 v[100:103], v86 offset:32768
	ds_read_b128 v[144:147], v86 offset:36864
	ds_read_b128 v[148:151], v88 offset:32768
	ds_read_b128 v[152:155], v88 offset:36864
	ds_read_b128 v[180:183], v90 offset:32768
	ds_read_b128 v[184:187], v90 offset:36864
	s_waitcnt lgkmcnt(6)
	v_mfma_f32_32x32x16_bf16 v[104:119], v[92:95], v[188:191], v[104:119]
	v_mfma_f32_32x32x16_bf16 v[128:143], v[92:95], v[192:195], v[128:143]
	v_mfma_f32_32x32x16_bf16 v[196:211], v[96:99], v[188:191], v[196:211]
	v_mfma_f32_32x32x16_bf16 v[236:251], v[96:99], v[192:195], v[236:251]
	s_waitcnt lgkmcnt(0)
	s_barrier
	v_mfma_f32_32x32x16_bf16 v[104:119], v[100:103], v[212:215], v[104:119]
	s_mov_b32 m0, s6
	v_lshl_add_u64 v[82:83], v[66:67], 0, s[26:27]
	v_mfma_f32_32x32x16_bf16 v[128:143], v[100:103], v[216:219], v[128:143]
	global_load_lds_dwordx4 v[82:83], off
	v_lshl_add_u64 v[66:67], v[66:67], 0, s[34:35]
	v_mfma_f32_32x32x16_bf16 v[196:211], v[144:147], v[212:215], v[196:211]
	s_mov_b32 m0, s13
	v_lshl_add_u64 v[82:83], v[70:71], 0, s[26:27]
	v_mfma_f32_32x32x16_bf16 v[236:251], v[144:147], v[216:219], v[236:251]
	global_load_lds_dwordx4 v[82:83], off
	v_lshl_add_u64 v[70:71], v[70:71], 0, s[34:35]
	v_mfma_f32_32x32x16_bf16 v[104:119], v[148:151], v[220:223], v[104:119]
	s_mov_b32 m0, s15
	v_lshl_add_u64 v[82:83], v[74:75], 0, s[26:27]
	v_mfma_f32_32x32x16_bf16 v[128:143], v[148:151], v[224:227], v[128:143]
	global_load_lds_dwordx4 v[82:83], off
	v_lshl_add_u64 v[74:75], v[74:75], 0, s[34:35]
	v_mfma_f32_32x32x16_bf16 v[196:211], v[152:155], v[220:223], v[196:211]
	s_mov_b32 m0, s17
	v_lshl_add_u64 v[82:83], v[78:79], 0, s[26:27]
	v_mfma_f32_32x32x16_bf16 v[236:251], v[152:155], v[224:227], v[236:251]
	global_load_lds_dwordx4 v[82:83], off
	v_lshl_add_u64 v[78:79], v[78:79], 0, s[34:35]
	v_mfma_f32_32x32x16_bf16 v[104:119], v[180:183], v[228:231], v[104:119]
	s_mov_b32 m0, s16
	v_mfma_f32_32x32x16_bf16 v[128:143], v[180:183], v[252:255], v[128:143]
	global_load_lds_dwordx4 v[76:77], off
	v_lshl_add_u64 v[76:77], v[76:77], 0, s[34:35]
	v_mfma_f32_32x32x16_bf16 v[196:211], v[184:187], v[228:231], v[196:211]
	s_mov_b32 m0, s25
	v_mfma_f32_32x32x16_bf16 v[236:251], v[184:187], v[252:255], v[236:251]
	global_load_lds_dwordx4 v[80:81], off
	v_lshl_add_u64 v[80:81], v[80:81], 0, s[34:35]
	s_waitcnt vmcnt(6)
	s_barrier
	s_add_i32 s12, s12, 2
	s_cmp_lt_u32 s12, 14
	s_cbranch_scc1 .Lg1_loop_w3
	ds_read_b128 v[92:95], v84 offset:0
	ds_read_b128 v[96:99], v84 offset:4096
	ds_read_b128 v[188:191], v85 offset:0
	ds_read_b128 v[192:195], v85 offset:4096
	ds_read_b128 v[100:103], v86 offset:0
	ds_read_b128 v[144:147], v86 offset:4096
	ds_read_b128 v[212:215], v87 offset:0
	ds_read_b128 v[216:219], v87 offset:4096
	ds_read_b128 v[148:151], v88 offset:0
	ds_read_b128 v[152:155], v88 offset:4096
	ds_read_b128 v[220:223], v89 offset:0
	ds_read_b128 v[224:227], v89 offset:4096
	ds_read_b128 v[180:183], v90 offset:0
	ds_read_b128 v[184:187], v90 offset:4096
	ds_read_b128 v[228:231], v91 offset:0
	ds_read_b128 v[252:255], v91 offset:4096
	s_waitcnt lgkmcnt(12)
	v_mfma_f32_32x32x16_bf16 v[18:33], v[92:95], v[188:191], v[18:33]
	v_mfma_f32_32x32x16_bf16 v[50:65], v[92:95], v[192:195], v[50:65]
	v_mfma_f32_32x32x16_bf16 v[2:17], v[96:99], v[188:191], v[2:17]
	v_mfma_f32_32x32x16_bf16 v[34:49], v[96:99], v[192:195], v[34:49]
	s_waitcnt lgkmcnt(0)
	s_barrier
	v_mfma_f32_32x32x16_bf16 v[18:33], v[100:103], v[212:215], v[18:33]
	s_mov_b32 m0, s1
	v_mfma_f32_32x32x16_bf16 v[50:65], v[100:103], v[216:219], v[50:65]
	global_load_lds_dwordx4 v[66:67], off
	v_mfma_f32_32x32x16_bf16 v[2:17], v[144:147], v[212:215], v[2:17]
	s_add_i32 m0, s1, 0x400
	v_mfma_f32_32x32x16_bf16 v[34:49], v[144:147], v[216:219], v[34:49]
	global_load_lds_dwordx4 v[70:71], off
	v_mfma_f32_32x32x16_bf16 v[18:33], v[148:151], v[220:223], v[18:33]
	v_mfma_f32_32x32x16_bf16 v[50:65], v[148:151], v[224:227], v[50:65]
	v_mfma_f32_32x32x16_bf16 v[2:17], v[152:155], v[220:223], v[2:17]
	s_add_i32 m0, s1, 0x800
	v_mfma_f32_32x32x16_bf16 v[34:49], v[152:155], v[224:227], v[34:49]
	global_load_lds_dwordx4 v[74:75], off
	v_mfma_f32_32x32x16_bf16 v[18:33], v[180:183], v[228:231], v[18:33]
	s_add_i32 m0, s1, 0xc00
	v_mfma_f32_32x32x16_bf16 v[50:65], v[180:183], v[252:255], v[50:65]
	global_load_lds_dwordx4 v[78:79], off
	v_mfma_f32_32x32x16_bf16 v[2:17], v[184:187], v[228:231], v[2:17]
	v_mfma_f32_32x32x16_bf16 v[34:49], v[184:187], v[252:255], v[34:49]
	s_waitcnt vmcnt(4)
	s_barrier
	ds_read_b128 v[92:95], v84 offset:32768
	ds_read_b128 v[96:99], v84 offset:36864
	ds_read_b128 v[100:103], v86 offset:32768
	ds_read_b128 v[144:147], v86 offset:36864
	ds_read_b128 v[148:151], v88 offset:32768
	ds_read_b128 v[152:155], v88 offset:36864
	ds_read_b128 v[180:183], v90 offset:32768
	ds_read_b128 v[184:187], v90 offset:36864
	s_waitcnt lgkmcnt(6)
	v_mfma_f32_32x32x16_bf16 v[104:119], v[92:95], v[188:191], v[104:119]
	v_mfma_f32_32x32x16_bf16 v[128:143], v[92:95], v[192:195], v[128:143]
	v_mfma_f32_32x32x16_bf16 v[196:211], v[96:99], v[188:191], v[196:211]
	v_mfma_f32_32x32x16_bf16 v[236:251], v[96:99], v[192:195], v[236:251]
	s_waitcnt lgkmcnt(0)
	s_barrier
	v_mfma_f32_32x32x16_bf16 v[104:119], v[100:103], v[212:215], v[104:119]
	s_mov_b32 m0, s6
	v_lshl_add_u64 v[82:83], v[66:67], 0, s[26:27]
	v_mfma_f32_32x32x16_bf16 v[128:143], v[100:103], v[216:219], v[128:143]
	global_load_lds_dwordx4 v[82:83], off
	v_lshl_add_u64 v[66:67], v[66:67], 0, s[34:35]
	v_mfma_f32_32x32x16_bf16 v[196:211], v[144:147], v[212:215], v[196:211]
	s_mov_b32 m0, s13
	v_lshl_add_u64 v[82:83], v[70:71], 0, s[26:27]
	v_mfma_f32_32x32x16_bf16 v[236:251], v[144:147], v[216:219], v[236:251]
	global_load_lds_dwordx4 v[82:83], off
	v_lshl_add_u64 v[70:71], v[70:71], 0, s[34:35]
	v_mfma_f32_32x32x16_bf16 v[104:119], v[148:151], v[220:223], v[104:119]
	v_mfma_f32_32x32x16_bf16 v[128:143], v[148:151], v[224:227], v[128:143]
	v_mfma_f32_32x32x16_bf16 v[196:211], v[152:155], v[220:223], v[196:211]
	s_mov_b32 m0, s15
	v_lshl_add_u64 v[82:83], v[74:75], 0, s[26:27]
	v_mfma_f32_32x32x16_bf16 v[236:251], v[152:155], v[224:227], v[236:251]
	global_load_lds_dwordx4 v[82:83], off
	v_lshl_add_u64 v[74:75], v[74:75], 0, s[34:35]
	v_mfma_f32_32x32x16_bf16 v[104:119], v[180:183], v[228:231], v[104:119]
	s_mov_b32 m0, s17
	v_lshl_add_u64 v[82:83], v[78:79], 0, s[26:27]
	v_mfma_f32_32x32x16_bf16 v[128:143], v[180:183], v[252:255], v[128:143]
	global_load_lds_dwordx4 v[82:83], off
	v_lshl_add_u64 v[78:79], v[78:79], 0, s[34:35]
	v_mfma_f32_32x32x16_bf16 v[196:211], v[184:187], v[228:231], v[196:211]
	v_mfma_f32_32x32x16_bf16 v[236:251], v[184:187], v[252:255], v[236:251]
	s_waitcnt vmcnt(4)
	s_barrier
	ds_read_b128 v[92:95], v84 offset:0
	ds_read_b128 v[96:99], v84 offset:4096
	ds_read_b128 v[188:191], v85 offset:32768
	ds_read_b128 v[192:195], v85 offset:36864
	ds_read_b128 v[100:103], v86 offset:0
	ds_read_b128 v[144:147], v86 offset:4096
	ds_read_b128 v[212:215], v87 offset:32768
	ds_read_b128 v[216:219], v87 offset:36864
	ds_read_b128 v[148:151], v88 offset:0
	ds_read_b128 v[152:155], v88 offset:4096
	ds_read_b128 v[220:223], v89 offset:32768
	ds_read_b128 v[224:227], v89 offset:36864
	ds_read_b128 v[180:183], v90 offset:0
	ds_read_b128 v[184:187], v90 offset:4096
	ds_read_b128 v[228:231], v91 offset:32768
	ds_read_b128 v[252:255], v91 offset:36864
	s_waitcnt lgkmcnt(12)
	v_mfma_f32_32x32x16_bf16 v[18:33], v[92:95], v[188:191], v[18:33]
	v_mfma_f32_32x32x16_bf16 v[50:65], v[92:95], v[192:195], v[50:65]
	v_mfma_f32_32x32x16_bf16 v[2:17], v[96:99], v[188:191], v[2:17]
	v_mfma_f32_32x32x16_bf16 v[34:49], v[96:99], v[192:195], v[34:49]
	s_waitcnt lgkmcnt(0)
	s_barrier
	v_mfma_f32_32x32x16_bf16 v[18:33], v[100:103], v[212:215], v[18:33]
	v_mfma_f32_32x32x16_bf16 v[50:65], v[100:103], v[216:219], v[50:65]
	v_mfma_f32_32x32x16_bf16 v[2:17], v[144:147], v[212:215], v[2:17]
	v_mfma_f32_32x32x16_bf16 v[34:49], v[144:147], v[216:219], v[34:49]
	v_mfma_f32_32x32x16_bf16 v[18:33], v[148:151], v[220:223], v[18:33]
	v_mfma_f32_32x32x16_bf16 v[50:65], v[148:151], v[224:227], v[50:65]
	v_mfma_f32_32x32x16_bf16 v[2:17], v[152:155], v[220:223], v[2:17]
	v_mfma_f32_32x32x16_bf16 v[34:49], v[152:155], v[224:227], v[34:49]
	v_mfma_f32_32x32x16_bf16 v[18:33], v[180:183], v[228:231], v[18:33]
	v_mfma_f32_32x32x16_bf16 v[50:65], v[180:183], v[252:255], v[50:65]
	v_mfma_f32_32x32x16_bf16 v[2:17], v[184:187], v[228:231], v[2:17]
	v_mfma_f32_32x32x16_bf16 v[34:49], v[184:187], v[252:255], v[34:49]
	s_waitcnt vmcnt(0)
	s_barrier
	ds_read_b128 v[92:95], v84 offset:32768
	ds_read_b128 v[96:99], v84 offset:36864
	ds_read_b128 v[100:103], v86 offset:32768
	ds_read_b128 v[144:147], v86 offset:36864
	ds_read_b128 v[148:151], v88 offset:32768
	ds_read_b128 v[152:155], v88 offset:36864
	ds_read_b128 v[180:183], v90 offset:32768
	ds_read_b128 v[184:187], v90 offset:36864
	s_waitcnt lgkmcnt(6)
	v_mfma_f32_32x32x16_bf16 v[104:119], v[92:95], v[188:191], v[104:119]
	v_mfma_f32_32x32x16_bf16 v[128:143], v[92:95], v[192:195], v[128:143]
	v_mfma_f32_32x32x16_bf16 v[196:211], v[96:99], v[188:191], v[196:211]
	v_mfma_f32_32x32x16_bf16 v[236:251], v[96:99], v[192:195], v[236:251]
	s_waitcnt lgkmcnt(0)
	s_barrier
	v_mfma_f32_32x32x16_bf16 v[104:119], v[100:103], v[212:215], v[104:119]
	v_mfma_f32_32x32x16_bf16 v[128:143], v[100:103], v[216:219], v[128:143]
	v_mfma_f32_32x32x16_bf16 v[196:211], v[144:147], v[212:215], v[196:211]
	v_mfma_f32_32x32x16_bf16 v[236:251], v[144:147], v[216:219], v[236:251]
	v_mfma_f32_32x32x16_bf16 v[104:119], v[148:151], v[220:223], v[104:119]
	v_mfma_f32_32x32x16_bf16 v[128:143], v[148:151], v[224:227], v[128:143]
	v_mfma_f32_32x32x16_bf16 v[196:211], v[152:155], v[220:223], v[196:211]
	v_mfma_f32_32x32x16_bf16 v[236:251], v[152:155], v[224:227], v[236:251]
	v_mfma_f32_32x32x16_bf16 v[104:119], v[180:183], v[228:231], v[104:119]
	v_mfma_f32_32x32x16_bf16 v[128:143], v[180:183], v[252:255], v[128:143]
	v_mfma_f32_32x32x16_bf16 v[196:211], v[184:187], v[228:231], v[196:211]
	v_mfma_f32_32x32x16_bf16 v[236:251], v[184:187], v[252:255], v[236:251]
	s_waitcnt vmcnt(0) lgkmcnt(0)
	s_barrier
